# MLA attention loop: negm as MFMA C operand (no copies), split max chain, simpler update test, P operand without permlane (V read layout), static prio waves 4-7
# speedup vs baseline: 1.0060x; 1.0060x over previous
.LBB0_912:
	s_waitcnt vmcnt(0)
	s_cmp_lt_i32 s26, 1
	v_cmp_gt_u32_e64 s[36:37], 32, v176
	v_lshlrev_b32_e32 v191, 2, v177
	s_barrier
	s_cbranch_scc1 .LBB0_935
	v_bitop3_b32 v0, v51, v177, 7 bitop3:0x6c
	v_lshlrev_b32_e32 v193, 4, v0
	v_add_u32_e32 v0, 2, v177
	v_bitop3_b32 v0, v0, v51, 7 bitop3:0x78
	v_lshlrev_b32_e32 v210, 4, v0
	v_add_u32_e32 v0, 4, v177
	v_bitop3_b32 v0, v0, v51, 7 bitop3:0x78
	v_lshlrev_b32_e32 v211, 4, v0
	v_add_u32_e32 v0, 6, v177
	v_bitop3_b32 v0, v0, v51, 7 bitop3:0x78
	v_lshlrev_b32_e32 v212, 4, v0
	v_lshlrev_b32_e32 v0, 1, v176
	v_and_b32_e32 v2, 0x118, v50
	v_lshlrev_b32_e32 v3, 4, v176
	v_and_b32_e32 v3, 0xc0, v3
	v_and_or_b32 v0, v0, 32, v2
	s_add_i32 s0, 0, 0x6000
	v_add3_u32 v214, v3, s0, v0
	v_and_b32_e32 v225, 32, v176
	v_mad_u32_u24 v214, v225, 56, v214
	s_lshl_b32 s0, s94, 6
	s_ashr_i32 s1, s0, 31
	s_add_i32 s85, s26, -2
	s_mov_b32 s10, s84
	s_sub_i32 s84, s27, 64
	s_ashr_i32 s92, s9, 6
	s_sub_i32 s93, s27, 32
	s_lshl_b64 s[2:3], s[0:1], 11
	s_add_u32 s1, s2, s4
	s_addc_u32 s2, s3, s5
	s_add_u32 s1, s1, s8
	s_addc_u32 s2, s2, 0
	v_readlane_b32 s3, v254, 17
	s_add_u32 s88, s3, s1
	v_readlane_b32 s1, v254, 18
	s_addc_u32 s89, s1, s2
	s_mul_i32 s1, s94, 0x18000
	s_mul_hi_i32 s2, s0, 0x600
	s_add_u32 s1, s1, s7
	s_addc_u32 s2, s2, s6
	s_mul_i32 s3, s10, 0x180
	s_add_u32 s1, s1, s3
	v_writelane_b32 v255, s18, 33
	v_readlane_b32 s9, v254, 53
	s_waitcnt vmcnt(5)
	v_lshlrev_b32_e32 v16, 4, v177
	s_addc_u32 s2, s2, 0
	v_readlane_b32 s3, v254, 19
	v_mov_b32_e32 v14, v1
	v_mov_b32_e32 v15, v1
	v_writelane_b32 v255, s94, 34
	s_add_u32 s20, s3, s1
	v_readlane_b32 s1, v254, 20
	v_mov_b32_e32 v0, v1
	v_mov_b32_e32 v2, v1
	v_mov_b32_e32 v3, v1
	v_mov_b32_e32 v4, v1
	v_mov_b32_e32 v5, v1
	v_mov_b32_e32 v6, v1
	v_mov_b32_e32 v7, v1
	v_mov_b32_e32 v8, v1
	v_mov_b32_e32 v9, v1
	v_mov_b32_e32 v10, v1
	v_mov_b32_e32 v11, v1
	v_mov_b32_e32 v12, v1
	v_mov_b32_e32 v13, v1
	v_mov_b32_e32 v188, 0
	v_add_u32_e32 v215, s9, v16
	s_waitcnt vmcnt(1)
	v_mov_b64_e32 v[30:31], v[14:15]
	s_waitcnt vmcnt(0)
	v_mov_b64_e32 v[46:47], v[14:15]
	v_mov_b64_e32 v[62:63], v[14:15]
	v_mov_b64_e32 v[78:79], v[14:15]
	v_mul_u32_u24_e32 v192, 0x180, v190
	s_mov_b32 s34, 2
	v_lshl_add_u32 v213, v190, 2, s9
	v_writelane_b32 v255, s10, 35
	s_addc_u32 s21, s1, s2
	s_mov_b32 s25, 0
	s_mov_b64 s[18:19], -1
	v_mov_b64_e32 v[28:29], v[12:13]
	v_mov_b64_e32 v[26:27], v[10:11]
	v_mov_b64_e32 v[24:25], v[8:9]
	v_mov_b64_e32 v[22:23], v[6:7]
	v_mov_b64_e32 v[20:21], v[4:5]
	v_mov_b64_e32 v[18:19], v[2:3]
	v_mov_b64_e32 v[16:17], v[0:1]
	v_mov_b64_e32 v[44:45], v[12:13]
	v_mov_b64_e32 v[42:43], v[10:11]
	v_mov_b64_e32 v[40:41], v[8:9]
	v_mov_b64_e32 v[38:39], v[6:7]
	v_mov_b64_e32 v[36:37], v[4:5]
	v_mov_b64_e32 v[34:35], v[2:3]
	v_mov_b64_e32 v[32:33], v[0:1]
	v_mov_b64_e32 v[60:61], v[12:13]
	v_mov_b64_e32 v[58:59], v[10:11]
	v_mov_b64_e32 v[56:57], v[8:9]
	v_mov_b64_e32 v[54:55], v[6:7]
	v_mov_b64_e32 v[52:53], v[4:5]
	v_mov_b64_e32 v[50:51], v[2:3]
	v_mov_b64_e32 v[48:49], v[0:1]
	v_mov_b64_e32 v[76:77], v[12:13]
	v_mov_b64_e32 v[74:75], v[10:11]
	v_mov_b64_e32 v[72:73], v[8:9]
	v_mov_b64_e32 v[70:71], v[6:7]
	v_mov_b64_e32 v[68:69], v[4:5]
	v_mov_b64_e32 v[66:67], v[2:3]
	v_mov_b64_e32 v[64:65], v[0:1]
	v_mov_b32_e32 v189, 0
	s_mov_b32 s96, 0
	v_mov_b32_e32 v80, 0
	v_mov_b32_e32 v81, v188
	v_mov_b32_e32 v82, v188
	v_mov_b32_e32 v83, v188
	v_mov_b32_e32 v84, v188
	v_mov_b32_e32 v85, v188
	v_mov_b32_e32 v86, v188
	v_mov_b32_e32 v87, v188
	v_mov_b32_e32 v88, v188
	v_mov_b32_e32 v89, v188
	v_mov_b32_e32 v90, v188
	v_mov_b32_e32 v91, v188
	v_mov_b32_e32 v92, v188
	v_mov_b32_e32 v93, v188
	v_mov_b32_e32 v94, v188
	v_mov_b32_e32 v95, v188
	s_lshr_b32 s1, s56, 10
	s_cmp_ge_u32 s1, 4
	s_cbranch_scc0 .Lmla_prio_done
	s_setprio 1
.Lmla_prio_done:
	s_cmp_ge_i32 s96, s85
	s_cselect_b64 s[94:95], -1, 0
	s_and_b64 vcc, exec, s[94:95]
	s_cbranch_vccnz .LBB0_916
	s_branch .LBB0_915

.LBB0_916:
	s_sub_i32 s97, s0, 64
	s_cmp_le_i32 s35, s92
	s_cselect_b64 s[2:3], -1, 0
	s_and_b64 s[2:3], s[2:3], s[86:87]
	s_andn2_b64 vcc, exec, s[2:3]
	s_cbranch_vccnz .LBB0_923
	s_mul_i32 s2, s25, 0xa100
	s_add_i32 s1, s2, 0
	v_add3_u32 v0, s1, v193, v192
	v_add3_u32 v14, s1, v210, v192
	ds_read_b128 v[2:5], v0
	ds_read_b128 v[6:9], v0 offset:12288
	ds_read_b128 v[10:13], v14
	ds_read_b128 v[194:197], v14 offset:12288
	s_cmp_le_i32 s97, s84
	v_add3_u32 v15, s1, v211, v192
	v_add3_u32 v220, s1, v212, v192
	ds_read_b128 v[198:201], v15
	ds_read_b128 v[202:205], v15 offset:12288
	ds_read_b128 v[206:209], v220
	ds_read_b128 v[216:219], v220 offset:12288
	s_waitcnt lgkmcnt(7)
	v_mfma_f32_32x32x16_bf16 v[96:111], v[2:5], v[128:131], v[80:95]
	s_waitcnt lgkmcnt(6)
	v_mfma_f32_32x32x16_bf16 v[112:127], v[6:9], v[128:131], v[80:95]
	s_waitcnt lgkmcnt(5)
	v_mfma_f32_32x32x16_bf16 v[96:111], v[10:13], v[132:135], v[96:111]
	s_waitcnt lgkmcnt(4)
	v_mfma_f32_32x32x16_bf16 v[112:127], v[194:197], v[132:135], v[112:127]
	ds_read_b128 v[2:5], v14 offset:12416
	ds_read_b128 v[6:9], v14 offset:128
	ds_read_b128 v[10:13], v0 offset:12416
	ds_read_b128 v[194:197], v0 offset:128
	s_waitcnt lgkmcnt(7)
	v_mfma_f32_32x32x16_bf16 v[96:111], v[198:201], v[136:139], v[96:111]
	s_waitcnt lgkmcnt(6)
	v_mfma_f32_32x32x16_bf16 v[112:127], v[202:205], v[136:139], v[112:127]
	s_waitcnt lgkmcnt(5)
	v_mfma_f32_32x32x16_bf16 v[96:111], v[206:209], v[140:143], v[96:111]
	s_waitcnt lgkmcnt(4)
	v_mfma_f32_32x32x16_bf16 v[112:127], v[216:219], v[140:143], v[112:127]
	ds_read_b128 v[198:201], v15 offset:128
	ds_read_b128 v[202:205], v15 offset:12416
	ds_read_b128 v[206:209], v220 offset:128
	ds_read_b128 v[216:219], v220 offset:12416
	s_waitcnt lgkmcnt(4)
	v_mfma_f32_32x32x16_bf16 v[96:111], v[194:197], v[144:147], v[96:111]
	v_mfma_f32_32x32x16_bf16 v[112:127], v[10:13], v[144:147], v[112:127]
	v_mfma_f32_32x32x16_bf16 v[96:111], v[6:9], v[148:151], v[96:111]
	v_mfma_f32_32x32x16_bf16 v[112:127], v[2:5], v[148:151], v[112:127]
	ds_read_b128 v[2:5], v14 offset:12544
	ds_read_b128 v[6:9], v14 offset:256
	ds_read_b128 v[10:13], v0 offset:12544
	ds_read_b128 v[194:197], v0 offset:256
	s_waitcnt lgkmcnt(7)
	v_mfma_f32_32x32x16_bf16 v[96:111], v[198:201], v[152:155], v[96:111]
	s_waitcnt lgkmcnt(6)
	v_mfma_f32_32x32x16_bf16 v[112:127], v[202:205], v[152:155], v[112:127]
	s_waitcnt lgkmcnt(5)
	v_mfma_f32_32x32x16_bf16 v[96:111], v[206:209], v[156:159], v[96:111]
	s_waitcnt lgkmcnt(4)
	v_mfma_f32_32x32x16_bf16 v[112:127], v[216:219], v[156:159], v[112:127]
	ds_read_b128 v[198:201], v15 offset:256
	ds_read_b128 v[202:205], v15 offset:12544
	ds_read_b128 v[206:209], v220 offset:256
	ds_read_b128 v[216:219], v220 offset:12544
	s_waitcnt lgkmcnt(4)
	v_mfma_f32_32x32x16_bf16 v[96:111], v[194:197], v[160:163], v[96:111]
	v_mfma_f32_32x32x16_bf16 v[112:127], v[10:13], v[160:163], v[112:127]
	v_mfma_f32_32x32x16_bf16 v[96:111], v[6:9], v[168:171], v[96:111]
	v_mfma_f32_32x32x16_bf16 v[112:127], v[2:5], v[168:171], v[112:127]
	s_waitcnt lgkmcnt(3)
	v_mfma_f32_32x32x16_bf16 v[96:111], v[198:201], v[164:167], v[96:111]
	s_waitcnt lgkmcnt(2)
	v_mfma_f32_32x32x16_bf16 v[112:127], v[202:205], v[164:167], v[112:127]
	s_waitcnt lgkmcnt(1)
	v_mfma_f32_32x32x16_bf16 v[96:111], v[206:209], v[172:175], v[96:111]
	s_waitcnt lgkmcnt(0)
	v_mfma_f32_32x32x16_bf16 v[112:127], v[216:219], v[172:175], v[112:127]
	s_cbranch_scc1 .LBB0_919
	v_add_u32_e32 v0, s0, v191
	v_subrev_u32_e32 v2, 64, v0
	v_cmp_gt_i32_e64 s[52:53], s27, v2
	v_cmp_gt_i32_e32 vcc, s93, v2
	v_subrev_u32_e32 v2, 63, v0
	v_cmp_gt_i32_e64 s[54:55], s27, v2
	v_cmp_gt_i32_e64 s[0:1], s93, v2
	v_subrev_u32_e32 v2, 62, v0
	v_cmp_gt_i32_e64 s[56:57], s27, v2
	v_cmp_gt_i32_e64 s[14:15], s93, v2
	v_subrev_u32_e32 v2, 61, v0
	v_cmp_gt_i32_e64 s[58:59], s27, v2
	v_cmp_gt_i32_e64 s[4:5], s93, v2
	v_subrev_u32_e32 v2, 56, v0
	v_cmp_gt_i32_e64 s[60:61], s27, v2
	v_cmp_gt_i32_e64 s[6:7], s93, v2
	v_subrev_u32_e32 v2, 55, v0
	v_cmp_gt_i32_e64 s[62:63], s27, v2
	v_cmp_gt_i32_e64 s[8:9], s93, v2
	v_subrev_u32_e32 v2, 54, v0
	v_cmp_gt_i32_e64 s[64:65], s27, v2
	v_cmp_gt_i32_e64 s[10:11], s93, v2
	v_subrev_u32_e32 v2, 53, v0
	v_cmp_gt_i32_e64 s[66:67], s27, v2
	v_cmp_gt_i32_e64 s[12:13], s93, v2
	v_subrev_u32_e32 v2, 48, v0
	v_cmp_gt_i32_e64 s[68:69], s27, v2
	v_cmp_gt_i32_e64 s[38:39], s93, v2
	v_subrev_u32_e32 v2, 47, v0
	v_cmp_gt_i32_e64 s[70:71], s27, v2
	v_cmp_gt_i32_e64 s[40:41], s93, v2
	v_subrev_u32_e32 v2, 46, v0
	v_cmp_gt_i32_e64 s[72:73], s27, v2
	v_cmp_gt_i32_e64 s[42:43], s93, v2
	v_subrev_u32_e32 v2, 45, v0
	v_cmp_gt_i32_e64 s[74:75], s27, v2
	v_cmp_gt_i32_e64 s[44:45], s93, v2
	v_subrev_u32_e32 v2, 40, v0
	v_cmp_gt_i32_e64 s[76:77], s27, v2
	v_cmp_gt_i32_e64 s[46:47], s93, v2
	v_subrev_u32_e32 v2, 39, v0
	v_cmp_gt_i32_e64 s[78:79], s27, v2
	v_cmp_gt_i32_e64 s[48:49], s93, v2
	v_subrev_u32_e32 v2, 38, v0
	v_subrev_u32_e32 v0, 37, v0
	v_cmp_gt_i32_e64 s[80:81], s27, v2
	v_cmp_gt_i32_e64 s[82:83], s27, v0
	s_or_b64 s[80:81], s[82:83], s[80:81]
	s_or_b64 s[78:79], s[80:81], s[78:79]
	s_or_b64 s[76:77], s[78:79], s[76:77]
	s_or_b64 s[74:75], s[76:77], s[74:75]
	s_or_b64 s[72:73], s[74:75], s[72:73]
	s_or_b64 s[70:71], s[72:73], s[70:71]
	s_or_b64 s[68:69], s[70:71], s[68:69]
	s_or_b64 s[66:67], s[68:69], s[66:67]
	s_or_b64 s[64:65], s[66:67], s[64:65]
	s_or_b64 s[62:63], s[64:65], s[62:63]
	s_or_b64 s[60:61], s[62:63], s[60:61]
	s_or_b64 s[58:59], s[60:61], s[58:59]
	s_or_b64 s[56:57], s[58:59], s[56:57]
	s_or_b64 s[54:55], s[56:57], s[54:55]
	v_cmp_gt_i32_e64 s[50:51], s93, v2
	v_mov_b32_e32 v2, 0xff800000
	s_or_b64 s[52:53], s[54:55], s[52:53]
	v_cndmask_b32_e64 v96, v2, v96, s[52:53]
	v_cmp_gt_i32_e64 s[52:53], s93, v0
	s_or_b64 s[50:51], s[52:53], s[50:51]
	s_or_b64 s[48:49], s[50:51], s[48:49]
	s_or_b64 s[46:47], s[48:49], s[46:47]
	s_or_b64 s[44:45], s[46:47], s[44:45]
	s_or_b64 s[42:43], s[44:45], s[42:43]
	s_or_b64 s[40:41], s[42:43], s[40:41]
	s_or_b64 s[38:39], s[40:41], s[38:39]
	s_or_b64 s[12:13], s[38:39], s[12:13]
	s_or_b64 s[10:11], s[12:13], s[10:11]
	s_or_b64 s[8:9], s[10:11], s[8:9]
	s_or_b64 s[6:7], s[8:9], s[6:7]
	s_or_b64 s[4:5], s[6:7], s[4:5]
	v_cndmask_b32_e64 v115, v2, v115, s[4:5]
	s_or_b64 s[4:5], s[4:5], s[14:15]
	s_or_b64 s[0:1], s[4:5], s[0:1]
	s_or_b64 vcc, s[0:1], vcc
	v_cndmask_b32_e64 v111, v2, v111, s[82:83]
	v_cndmask_b32_e64 v110, v2, v110, s[80:81]
	v_cndmask_b32_e64 v109, v2, v109, s[78:79]
	v_cndmask_b32_e64 v108, v2, v108, s[76:77]
	v_cndmask_b32_e64 v107, v2, v107, s[74:75]
	v_cndmask_b32_e64 v106, v2, v106, s[72:73]
	v_cndmask_b32_e64 v105, v2, v105, s[70:71]
	v_cndmask_b32_e64 v104, v2, v104, s[68:69]
	v_cndmask_b32_e64 v103, v2, v103, s[66:67]
	v_cndmask_b32_e64 v102, v2, v102, s[64:65]
	v_cndmask_b32_e64 v101, v2, v101, s[62:63]
	v_cndmask_b32_e64 v100, v2, v100, s[60:61]
	v_cndmask_b32_e64 v99, v2, v99, s[58:59]
	v_cndmask_b32_e64 v98, v2, v98, s[56:57]
	v_readlane_b32 s57, v255, 15
	v_readlane_b32 s56, v255, 14
	v_cndmask_b32_e64 v97, v2, v97, s[54:55]
	v_cndmask_b32_e64 v127, v2, v127, s[52:53]
	v_cndmask_b32_e64 v126, v2, v126, s[50:51]
	v_cndmask_b32_e64 v125, v2, v125, s[48:49]
	v_cndmask_b32_e64 v124, v2, v124, s[46:47]
	v_cndmask_b32_e64 v123, v2, v123, s[44:45]
	v_cndmask_b32_e64 v122, v2, v122, s[42:43]
	v_cndmask_b32_e64 v121, v2, v121, s[40:41]
	v_cndmask_b32_e64 v120, v2, v120, s[38:39]
	v_cndmask_b32_e64 v119, v2, v119, s[12:13]
	v_cndmask_b32_e64 v118, v2, v118, s[10:11]
	v_cndmask_b32_e64 v117, v2, v117, s[8:9]
	v_cndmask_b32_e64 v116, v2, v116, s[6:7]
	v_cndmask_b32_e64 v114, v2, v114, s[4:5]
	v_cndmask_b32_e64 v113, v2, v113, s[0:1]
	v_cndmask_b32_e32 v112, v2, v112, vcc
.LBB0_919:
	s_nop 7
	v_max3_f32 v0, v96, v97, v98
	v_max3_f32 v2, v112, v113, v114
	v_max3_f32 v0, v0, v99, v100
	v_max3_f32 v2, v2, v115, v116
	v_max3_f32 v0, v0, v101, v102
	v_max3_f32 v2, v2, v117, v118
	v_max3_f32 v0, v0, v103, v104
	v_max3_f32 v2, v2, v119, v120
	v_max3_f32 v0, v0, v105, v106
	v_max3_f32 v2, v2, v121, v122
	v_max3_f32 v0, v0, v107, v108
	v_max3_f32 v2, v2, v123, v124
	v_max3_f32 v0, v0, v109, v110
	v_max3_f32 v2, v2, v125, v126
	v_max3_f32 v0, v0, v111, v127
	v_max_f32_e32 v0, v0, v2
	v_mov_b32_e32 v2, v0
	s_nop 1
	v_permlane32_swap_b32_e32 v0, v2
	v_max_f32_e32 v0, v0, v2
	v_cmp_lt_f32_e32 vcc, 0x41000000, v0
	s_or_b64 s[0:1], s[18:19], vcc
	v_cmp_lg_f32_e32 vcc, 0xff800000, v0
	s_and_b64 s[0:1], s[0:1], vcc
	s_cbranch_scc0 .LBB0_925
	v_cndmask_b32_e64 v0, 0, v0, s[0:1]
	v_exp_f32_e64 v2, -v0
	s_xor_b64 s[0:1], s[0:1], -1
	v_add_f32_e32 v188, v188, v0
	s_or_b64 s[4:5], s[0:1], s[18:19]
	s_and_b64 s[0:1], s[18:19], s[0:1]
	v_xor_b32_e32 v80, 0x80000000, v188
	v_pk_add_f32 v[96:97], v[96:97], v[0:1] op_sel_hi:[1,0] neg_lo:[0,1] neg_hi:[0,1]
	v_pk_add_f32 v[112:113], v[112:113], v[0:1] op_sel_hi:[1,0] neg_lo:[0,1] neg_hi:[0,1]
	v_pk_add_f32 v[98:99], v[98:99], v[0:1] op_sel_hi:[1,0] neg_lo:[0,1] neg_hi:[0,1]
	v_pk_add_f32 v[114:115], v[114:115], v[0:1] op_sel_hi:[1,0] neg_lo:[0,1] neg_hi:[0,1]
	v_pk_add_f32 v[100:101], v[100:101], v[0:1] op_sel_hi:[1,0] neg_lo:[0,1] neg_hi:[0,1]
	v_pk_add_f32 v[116:117], v[116:117], v[0:1] op_sel_hi:[1,0] neg_lo:[0,1] neg_hi:[0,1]
	v_pk_add_f32 v[102:103], v[102:103], v[0:1] op_sel_hi:[1,0] neg_lo:[0,1] neg_hi:[0,1]
	v_pk_add_f32 v[118:119], v[118:119], v[0:1] op_sel_hi:[1,0] neg_lo:[0,1] neg_hi:[0,1]
	v_pk_add_f32 v[104:105], v[104:105], v[0:1] op_sel_hi:[1,0] neg_lo:[0,1] neg_hi:[0,1]
	v_pk_add_f32 v[120:121], v[120:121], v[0:1] op_sel_hi:[1,0] neg_lo:[0,1] neg_hi:[0,1]
	v_pk_add_f32 v[106:107], v[106:107], v[0:1] op_sel_hi:[1,0] neg_lo:[0,1] neg_hi:[0,1]
	v_pk_add_f32 v[122:123], v[122:123], v[0:1] op_sel_hi:[1,0] neg_lo:[0,1] neg_hi:[0,1]
	v_pk_add_f32 v[108:109], v[108:109], v[0:1] op_sel_hi:[1,0] neg_lo:[0,1] neg_hi:[0,1]
	v_pk_add_f32 v[124:125], v[124:125], v[0:1] op_sel_hi:[1,0] neg_lo:[0,1] neg_hi:[0,1]
	v_pk_add_f32 v[110:111], v[110:111], v[0:1] op_sel_hi:[1,0] neg_lo:[0,1] neg_hi:[0,1]
	v_pk_add_f32 v[126:127], v[126:127], v[0:1] op_sel_hi:[1,0] neg_lo:[0,1] neg_hi:[0,1]
	v_cndmask_b32_e64 v0, v2, 1.0, s[4:5]
	s_andn2_b64 s[4:5], s[18:19], exec
	s_and_b64 s[0:1], s[0:1], exec
	s_or_b64 s[18:19], s[4:5], s[0:1]
	v_mov_b32_e32 v81, v80
	v_mov_b32_e32 v82, v80
	v_mov_b32_e32 v83, v80
	v_mov_b32_e32 v84, v80
	v_mov_b32_e32 v85, v80
	v_mov_b32_e32 v86, v80
	v_mov_b32_e32 v87, v80
	v_mov_b32_e32 v88, v80
	v_mov_b32_e32 v89, v80
	v_mov_b32_e32 v90, v80
	v_mov_b32_e32 v91, v80
	v_mov_b32_e32 v92, v80
	v_mov_b32_e32 v93, v80
	v_mov_b32_e32 v94, v80
	v_mov_b32_e32 v95, v80
	s_branch .LBB0_926

.LBB0_930:
	v_add_f32_e32 v118, v110, v111
	v_cvt_pk_bf16_f32 v2, v2, v3
	v_cvt_pk_bf16_f32 v3, v4, v5
	v_cvt_pk_bf16_f32 v4, v112, v113
	v_cvt_pk_bf16_f32 v5, v114, v115
	v_cvt_pk_bf16_f32 v102, v102, v103
	v_cvt_pk_bf16_f32 v103, v104, v105
	v_cvt_pk_bf16_f32 v104, v106, v107
	v_cvt_pk_bf16_f32 v105, v108, v109
	v_cvt_pk_bf16_f32 v6, v6, v7
	v_cvt_pk_bf16_f32 v7, v8, v9
	v_cvt_pk_bf16_f32 v8, v10, v11
	v_cvt_pk_bf16_f32 v9, v13, v15
	v_cvt_pk_bf16_f32 v10, v12, v14
	v_cvt_pk_bf16_f32 v11, v96, v97
	v_cvt_pk_bf16_f32 v12, v98, v99
	v_cvt_pk_bf16_f32 v13, v100, v101
	v_fmac_f32_e32 v118, v189, v0
	v_add_u32_e32 v0, s2, v214
	ds_read_b64_tr_b16 v[96:97], v0 offset:0x0
	ds_read_b64_tr_b16 v[98:99], v0 offset:0x100
	ds_read_b64_tr_b16 v[106:107], v0 offset:0x1000
	ds_read_b64_tr_b16 v[108:109], v0 offset:0x1100
	ds_read_b64_tr_b16 v[110:111], v0 offset:0x2000
	ds_read_b64_tr_b16 v[112:113], v0 offset:0x2100
	ds_read_b64_tr_b16 v[114:115], v0 offset:0x3000
	ds_read_b64_tr_b16 v[116:117], v0 offset:0x3100
	s_waitcnt lgkmcnt(0)
	s_nop 0
	v_mfma_f32_32x32x16_bf16 v[64:79], v[2:5], v[96:99], v[64:79]
	ds_read_b64_tr_b16 v[96:97], v0 offset:0x200
	ds_read_b64_tr_b16 v[98:99], v0 offset:0x300
	v_mfma_f32_32x32x16_bf16 v[64:79], v[102:105], v[106:109], v[64:79]
	ds_read_b64_tr_b16 v[106:107], v0 offset:0x1200
	ds_read_b64_tr_b16 v[108:109], v0 offset:0x1300
	v_mfma_f32_32x32x16_bf16 v[64:79], v[6:9], v[110:113], v[64:79]
	ds_read_b64_tr_b16 v[110:111], v0 offset:0x2200
	ds_read_b64_tr_b16 v[112:113], v0 offset:0x2300
	v_mfma_f32_32x32x16_bf16 v[64:79], v[10:13], v[114:117], v[64:79]
	ds_read_b64_tr_b16 v[114:115], v0 offset:0x3200
	ds_read_b64_tr_b16 v[116:117], v0 offset:0x3300
	s_waitcnt lgkmcnt(0)
	v_mfma_f32_32x32x16_bf16 v[48:63], v[2:5], v[96:99], v[48:63]
	ds_read_b64_tr_b16 v[96:97], v0 offset:0x400
	ds_read_b64_tr_b16 v[98:99], v0 offset:0x500
	v_mfma_f32_32x32x16_bf16 v[48:63], v[102:105], v[106:109], v[48:63]
	ds_read_b64_tr_b16 v[106:107], v0 offset:0x1400
	ds_read_b64_tr_b16 v[108:109], v0 offset:0x1500
	v_mfma_f32_32x32x16_bf16 v[48:63], v[6:9], v[110:113], v[48:63]
	ds_read_b64_tr_b16 v[110:111], v0 offset:0x2400
	ds_read_b64_tr_b16 v[112:113], v0 offset:0x2500
	v_mfma_f32_32x32x16_bf16 v[48:63], v[10:13], v[114:117], v[48:63]
	ds_read_b64_tr_b16 v[114:115], v0 offset:0x3400
	ds_read_b64_tr_b16 v[116:117], v0 offset:0x3500
	s_waitcnt lgkmcnt(0)
	v_mfma_f32_32x32x16_bf16 v[32:47], v[2:5], v[96:99], v[32:47]
	ds_read_b64_tr_b16 v[96:97], v0 offset:0x600
	ds_read_b64_tr_b16 v[98:99], v0 offset:0x700
	v_mfma_f32_32x32x16_bf16 v[32:47], v[102:105], v[106:109], v[32:47]
	ds_read_b64_tr_b16 v[106:107], v0 offset:0x1600
	ds_read_b64_tr_b16 v[108:109], v0 offset:0x1700
	v_mfma_f32_32x32x16_bf16 v[32:47], v[6:9], v[110:113], v[32:47]
	ds_read_b64_tr_b16 v[110:111], v0 offset:0x2600
	ds_read_b64_tr_b16 v[112:113], v0 offset:0x2700
	v_mfma_f32_32x32x16_bf16 v[32:47], v[10:13], v[114:117], v[32:47]
	ds_read_b64_tr_b16 v[114:115], v0 offset:0x3600
	ds_read_b64_tr_b16 v[116:117], v0 offset:0x3700
	s_waitcnt lgkmcnt(0)
	v_mfma_f32_32x32x16_bf16 v[16:31], v[2:5], v[96:99], v[16:31]
	v_mfma_f32_32x32x16_bf16 v[16:31], v[102:105], v[106:109], v[16:31]
	v_mfma_f32_32x32x16_bf16 v[16:31], v[6:9], v[110:113], v[16:31]
	v_mfma_f32_32x32x16_bf16 v[16:31], v[10:13], v[114:117], v[16:31]
	v_mov_b32_e32 v189, v118
	s_mov_b64 s[0:1], -1
	s_and_b64 vcc, exec, s[94:95]
	s_cbranch_vccnz .LBB0_924

.LBB0_933:
	s_add_i32 s0, s25, 1
	s_cmp_lg_u32 s25, 2
	s_cselect_b32 s25, s0, 0
	s_add_i32 s0, s34, 1
	s_cmp_lg_u32 s34, 2
	s_cselect_b32 s34, s0, 0
	s_add_i32 s96, s96, 1
	s_add_i32 s35, s35, -1
	s_add_u32 s88, s88, 0xfffe0000
	s_addc_u32 s89, s89, -1
	s_add_u32 s20, s20, 0xfffe8000
	s_addc_u32 s21, s21, -1
	s_cmp_ge_i32 s96, s26
	s_barrier
	s_cbranch_scc0 .LBB0_914
	s_setprio 0
	v_readlane_b32 s92, v255, 21
	v_readlane_b32 s94, v255, 34
	v_readlane_b32 s84, v255, 35
	v_readlane_b32 s18, v255, 33
	s_branch .LBB0_936

.LBB0_1088:
	s_nop 0
	v_readlane_b32 s0, v255, 30
	s_waitcnt vmcnt(4)
	v_lshlrev_b32_e32 v2, 1, v154
	s_add_i32 s27, s0, s55
	v_and_b32_e32 v2, 32, v2
	s_movk_i32 s0, 0x118
	v_and_or_b32 v0, v0, s0, v2
	v_lshlrev_b32_e32 v2, 4, v154
	v_and_b32_e32 v2, 0xc0, v2
	s_add_i32 s0, 0, 0x6000
	v_add3_u32 v159, v2, s0, v0
	v_and_b32_e32 v225, 32, v154
	v_mad_u32_u24 v159, v225, 56, v159
	v_lshlrev_b32_e32 v0, 8, v155
	v_bitop3_b32 v2, v156, v154, 15 bitop3:0x78
	v_lshl_add_u32 v160, v2, 4, v0
	v_add_u32_e32 v2, 2, v156
	v_bitop3_b32 v2, v2, v154, 15 bitop3:0x78
	v_lshl_add_u32 v161, v2, 4, v0
	v_add_u32_e32 v2, 4, v156
	s_add_i32 s36, s27, 31
	v_bitop3_b32 v2, v2, v154, 15 bitop3:0x78
	v_lshl_add_u32 v162, v2, 4, v0
	v_add_u32_e32 v2, 6, v156
	s_cmp_ge_i32 s4, s36
	v_bitop3_b32 v2, v2, v154, 15 bitop3:0x78
	s_cselect_b64 s[0:1], -1, 0
	v_lshl_add_u32 v163, v2, 4, v0
	s_or_b64 s[0:1], s[0:1], s[6:7]
	v_lshlrev_b32_e32 v158, 2, v156
	v_cmp_gt_u32_e64 s[38:39], 32, v154
	v_add_u32_e32 v164, s27, v155
	s_and_b64 vcc, exec, s[0:1]
	v_xor_b32_e32 v165, 0x80, v161
	v_xor_b32_e32 v166, 0x80, v160
	v_xor_b32_e32 v167, 0x80, v162
	v_xor_b32_e32 v168, 0x80, v163
	v_writelane_b32 v255, s17, 39
	s_cbranch_vccnz .LBB0_1091
	v_add_u32_e32 v0, 0, v160
	s_waitcnt vmcnt(1)
	ds_read_b128 v[2:5], v0
	s_waitcnt vmcnt(0)
	ds_read_b128 v[6:9], v0 offset:8192
	v_add_u32_e32 v0, 0, v161
	ds_read_b128 v[34:37], v0
	ds_read_b128 v[38:41], v0 offset:8192
	s_or_b32 s0, s4, 63
	s_cmp_lt_u32 s0, s27
	s_cselect_b64 s[18:19], -1, 0
	s_setprio 1
	v_add_u32_e32 v0, 0, v162
	ds_read_b128 v[42:45], v0
	ds_read_b128 v[46:49], v0 offset:8192
	v_add_u32_e32 v0, 0, v163
	ds_read_b128 v[50:53], v0
	ds_read_b128 v[54:57], v0 offset:8192
	s_waitcnt lgkmcnt(7)
	v_mfma_f32_32x32x16_bf16 v[18:33], v[2:5], v[112:115], 0
	s_waitcnt lgkmcnt(6)
	v_mfma_f32_32x32x16_bf16 v[2:17], v[6:9], v[112:115], 0
	s_waitcnt lgkmcnt(5)
	v_mfma_f32_32x32x16_bf16 v[18:33], v[34:37], v[116:119], v[18:33]
	s_waitcnt lgkmcnt(4)
	v_mfma_f32_32x32x16_bf16 v[2:17], v[38:41], v[116:119], v[2:17]
	v_add_u32_e32 v0, 0, v165
	ds_read_b128 v[34:37], v0 offset:8192
	ds_read_b128 v[38:41], v0
	v_add_u32_e32 v0, 0, v166
	ds_read_b128 v[58:61], v0 offset:8192
	ds_read_b128 v[62:65], v0
	s_waitcnt lgkmcnt(7)
	v_mfma_f32_32x32x16_bf16 v[18:33], v[42:45], v[120:123], v[18:33]
	s_waitcnt lgkmcnt(6)
	v_mfma_f32_32x32x16_bf16 v[2:17], v[46:49], v[120:123], v[2:17]
	s_waitcnt lgkmcnt(5)
	v_mfma_f32_32x32x16_bf16 v[18:33], v[50:53], v[124:127], v[18:33]
	s_waitcnt lgkmcnt(4)
	v_mfma_f32_32x32x16_bf16 v[2:17], v[54:57], v[124:127], v[2:17]
	v_add_u32_e32 v0, 0, v167
	ds_read_b128 v[42:45], v0
	ds_read_b128 v[46:49], v0 offset:8192
	v_add_u32_e32 v0, 0, v168
	ds_read_b128 v[50:53], v0
	ds_read_b128 v[54:57], v0 offset:8192
	s_waitcnt lgkmcnt(4)
	v_mfma_f32_32x32x16_bf16 v[18:33], v[62:65], v[128:131], v[18:33]
	v_mfma_f32_32x32x16_bf16 v[2:17], v[58:61], v[128:131], v[2:17]
	v_mfma_f32_32x32x16_bf16 v[18:33], v[38:41], v[132:135], v[18:33]
	v_mfma_f32_32x32x16_bf16 v[2:17], v[34:37], v[132:135], v[2:17]
	s_waitcnt lgkmcnt(3)
	v_mfma_f32_32x32x16_bf16 v[18:33], v[42:45], v[136:139], v[18:33]
	s_waitcnt lgkmcnt(2)
	v_mfma_f32_32x32x16_bf16 v[2:17], v[46:49], v[136:139], v[2:17]
	s_waitcnt lgkmcnt(1)
	v_mfma_f32_32x32x16_bf16 v[18:33], v[50:53], v[140:143], v[18:33]
	s_waitcnt lgkmcnt(0)
	v_mfma_f32_32x32x16_bf16 v[2:17], v[54:57], v[140:143], v[2:17]
	s_setprio 0
	v_add_u32_e32 v0, s4, v158
	v_add_u32_e32 v34, 32, v0
	s_mov_b32 s2, 0xbfb8aa3b
	v_cmp_lt_i32_e64 s[0:1], v34, v164
	s_nop 4
	v_mul_f32_e64 v34, |v18|, s2
	v_exp_f32_e32 v34, v34
	v_max_f32_e32 v35, v18, v18
	v_cmp_lt_i32_e32 vcc, v0, v164
	v_max_f32_e32 v35, 0, v35
	v_add_f32_e32 v34, 1.0, v34
	v_log_f32_e32 v34, v34
	v_mul_f32_e64 v36, |v2|, s2
	s_or_b64 vcc, s[18:19], vcc
	v_exp_f32_e32 v36, v36
	v_fmac_f32_e32 v35, 0x3f317218, v34
	v_max_f32_e32 v34, v2, v2
	v_max_f32_e32 v37, 0, v34
	v_cndmask_b32_e64 v34, 0, -v35, vcc
	v_or_b32_e32 v35, 1, v0
	v_cmp_lt_i32_e64 s[4:5], v35, v164
	v_add_u32_e32 v35, 33, v0
	v_cmp_lt_i32_e64 s[6:7], v35, v164
	v_mul_f32_e64 v35, |v19|, s2
	v_exp_f32_e32 v35, v35
	v_add_f32_e32 v36, 1.0, v36
	v_log_f32_e32 v36, v36
	s_or_b64 s[0:1], s[18:19], s[0:1]
	v_add_f32_e32 v35, 1.0, v35
	v_log_f32_e32 v35, v35
	v_fmac_f32_e32 v37, 0x3f317218, v36
	v_cndmask_b32_e64 v36, 0, -v37, s[0:1]
	v_max_f32_e32 v37, v19, v19
	v_max_f32_e32 v37, 0, v37
	v_mul_f32_e64 v38, |v3|, s2
	v_fmac_f32_e32 v37, 0x3f317218, v35
	v_max_f32_e32 v35, v3, v3
	s_or_b64 s[14:15], s[18:19], s[4:5]
	v_exp_f32_e32 v38, v38
	v_max_f32_e32 v39, 0, v35
	v_cndmask_b32_e64 v35, 0, -v37, s[14:15]
	v_or_b32_e32 v37, 2, v0
	s_or_b64 s[4:5], s[18:19], s[6:7]
	v_cmp_lt_i32_e64 s[6:7], v37, v164
	v_add_u32_e32 v37, 34, v0
	v_cmp_lt_i32_e64 s[8:9], v37, v164
	v_mul_f32_e64 v37, |v20|, s2
	v_exp_f32_e32 v37, v37
	v_add_f32_e32 v38, 1.0, v38
	v_log_f32_e32 v38, v38
	v_mul_f32_e64 v40, |v4|, s2
	v_add_f32_e32 v37, 1.0, v37
	v_log_f32_e32 v37, v37
	v_fmac_f32_e32 v39, 0x3f317218, v38
	v_cndmask_b32_e64 v38, 0, -v39, s[4:5]
	v_max_f32_e32 v39, v20, v20
	v_max_f32_e32 v39, 0, v39
	v_fmac_f32_e32 v39, 0x3f317218, v37
	v_max_f32_e32 v37, v4, v4
	s_or_b64 s[6:7], s[18:19], s[6:7]
	v_exp_f32_e32 v40, v40
	v_max_f32_e32 v41, 0, v37
	v_cndmask_b32_e64 v37, 0, -v39, s[6:7]
	v_or_b32_e32 v39, 3, v0
	v_cmp_lt_i32_e64 s[10:11], v39, v164
	v_add_u32_e32 v39, 35, v0
	v_cmp_lt_i32_e64 s[12:13], v39, v164
	v_mul_f32_e64 v39, |v21|, s2
	v_exp_f32_e32 v39, v39
	v_add_f32_e32 v40, 1.0, v40
	v_mul_f32_e64 v42, |v5|, s2
	v_log_f32_e32 v40, v40
	v_exp_f32_e32 v42, v42
	v_add_f32_e32 v39, 1.0, v39
	v_log_f32_e32 v39, v39
	v_fmac_f32_e32 v41, 0x3f317218, v40
	s_or_b64 s[8:9], s[18:19], s[8:9]
	v_add_f32_e32 v42, 1.0, v42
	v_cndmask_b32_e64 v40, 0, -v41, s[8:9]
	v_max_f32_e32 v41, v21, v21
	v_log_f32_e32 v42, v42
	v_max_f32_e32 v41, 0, v41
	v_fmac_f32_e32 v41, 0x3f317218, v39
	v_max_f32_e32 v39, v5, v5
	v_max_f32_e32 v43, 0, v39
	v_fmac_f32_e32 v43, 0x3f317218, v42
	v_add_u32_e32 v42, 8, v0
	v_cmp_lt_i32_e64 s[40:41], v42, v164
	v_add_u32_e32 v42, 40, v0
	v_cmp_lt_i32_e64 s[42:43], v42, v164
	v_mul_f32_e64 v42, |v22|, s2
	v_exp_f32_e32 v42, v42
	v_mul_f32_e64 v44, |v6|, s2
	v_exp_f32_e32 v44, v44
	s_or_b64 s[10:11], s[18:19], s[10:11]
	v_add_f32_e32 v42, 1.0, v42
	v_log_f32_e32 v42, v42
	s_or_b64 s[12:13], s[18:19], s[12:13]
	v_add_f32_e32 v44, 1.0, v44
	v_cndmask_b32_e64 v39, 0, -v41, s[10:11]
	v_cndmask_b32_e64 v41, 0, -v43, s[12:13]
	v_max_f32_e32 v43, v22, v22
	v_log_f32_e32 v44, v44
	v_max_f32_e32 v43, 0, v43
	v_fmac_f32_e32 v43, 0x3f317218, v42
	v_max_f32_e32 v42, v6, v6
	v_max_f32_e32 v42, 0, v42
	v_fmac_f32_e32 v42, 0x3f317218, v44
	s_or_b64 s[42:43], s[18:19], s[42:43]
	v_cndmask_b32_e64 v53, 0, -v42, s[42:43]
	v_add_u32_e32 v42, 9, v0
	v_cmp_lt_i32_e64 s[44:45], v42, v164
	v_add_u32_e32 v42, 41, v0
	v_cmp_lt_i32_e64 s[46:47], v42, v164
	v_mul_f32_e64 v42, |v23|, s2
	v_exp_f32_e32 v42, v42
	v_mul_f32_e64 v44, |v7|, s2
	v_exp_f32_e32 v44, v44
	s_or_b64 s[40:41], s[18:19], s[40:41]
	v_add_f32_e32 v42, 1.0, v42
	v_log_f32_e32 v42, v42
	v_add_f32_e32 v44, 1.0, v44
	v_cndmask_b32_e64 v51, 0, -v43, s[40:41]
	v_max_f32_e32 v43, v23, v23
	v_log_f32_e32 v44, v44
	v_max_f32_e32 v43, 0, v43
	v_fmac_f32_e32 v43, 0x3f317218, v42
	v_max_f32_e32 v42, v7, v7
	v_max_f32_e32 v42, 0, v42
	v_fmac_f32_e32 v42, 0x3f317218, v44
	s_or_b64 s[46:47], s[18:19], s[46:47]
	v_cndmask_b32_e64 v55, 0, -v42, s[46:47]
	v_add_u32_e32 v42, 10, v0
	v_cmp_lt_i32_e64 s[48:49], v42, v164
	v_add_u32_e32 v42, 42, v0
	v_cmp_lt_i32_e64 s[50:51], v42, v164
	v_mul_f32_e64 v42, |v24|, s2
	v_exp_f32_e32 v42, v42
	v_mul_f32_e64 v44, |v8|, s2
	v_exp_f32_e32 v44, v44
	s_or_b64 s[44:45], s[18:19], s[44:45]
	v_add_f32_e32 v42, 1.0, v42
	v_log_f32_e32 v42, v42
	v_add_f32_e32 v44, 1.0, v44
	v_cndmask_b32_e64 v56, 0, -v43, s[44:45]
	v_max_f32_e32 v43, v24, v24
	v_log_f32_e32 v44, v44
	v_max_f32_e32 v43, 0, v43
	v_fmac_f32_e32 v43, 0x3f317218, v42
	v_max_f32_e32 v42, v8, v8
	v_max_f32_e32 v42, 0, v42
	v_fmac_f32_e32 v42, 0x3f317218, v44
	s_or_b64 s[50:51], s[18:19], s[50:51]
	v_cndmask_b32_e64 v58, 0, -v42, s[50:51]
	v_add_u32_e32 v42, 11, v0
	v_cmp_lt_i32_e64 s[52:53], v42, v164
	v_add_u32_e32 v42, 43, v0
	v_cmp_lt_i32_e64 s[54:55], v42, v164
	v_mul_f32_e64 v42, |v25|, s2
	v_exp_f32_e32 v42, v42
	v_mul_f32_e64 v44, |v9|, s2
	v_exp_f32_e32 v44, v44
	s_or_b64 s[48:49], s[18:19], s[48:49]
	v_add_f32_e32 v42, 1.0, v42
	v_log_f32_e32 v42, v42
	v_add_f32_e32 v44, 1.0, v44
	v_cndmask_b32_e64 v57, 0, -v43, s[48:49]
	v_max_f32_e32 v43, v25, v25
	v_log_f32_e32 v44, v44
	v_max_f32_e32 v43, 0, v43
	v_fmac_f32_e32 v43, 0x3f317218, v42
	v_max_f32_e32 v42, v9, v9
	v_max_f32_e32 v42, 0, v42
	v_fmac_f32_e32 v42, 0x3f317218, v44
	s_or_b64 s[54:55], s[18:19], s[54:55]
	v_cndmask_b32_e64 v60, 0, -v42, s[54:55]
	v_add_u32_e32 v42, 16, v0
	v_cmp_lt_i32_e64 s[56:57], v42, v164
	v_add_u32_e32 v42, 48, v0
	v_cmp_lt_i32_e64 s[58:59], v42, v164
	v_mul_f32_e64 v42, |v26|, s2
	v_exp_f32_e32 v42, v42
	v_mul_f32_e64 v44, |v10|, s2
	v_exp_f32_e32 v44, v44
	s_or_b64 s[52:53], s[18:19], s[52:53]
	v_add_f32_e32 v42, 1.0, v42
	v_log_f32_e32 v42, v42
	v_add_f32_e32 v44, 1.0, v44
	v_cndmask_b32_e64 v59, 0, -v43, s[52:53]
	v_max_f32_e32 v43, v26, v26
	v_log_f32_e32 v44, v44
	v_max_f32_e32 v43, 0, v43
	v_fmac_f32_e32 v43, 0x3f317218, v42
	v_max_f32_e32 v42, v10, v10
	v_max_f32_e32 v42, 0, v42
	v_fmac_f32_e32 v42, 0x3f317218, v44
	s_or_b64 s[58:59], s[18:19], s[58:59]
	v_cndmask_b32_e64 v62, 0, -v42, s[58:59]
	v_add_u32_e32 v42, 17, v0
	v_cmp_lt_i32_e64 s[60:61], v42, v164
	v_add_u32_e32 v42, 49, v0
	v_cmp_lt_i32_e64 s[62:63], v42, v164
	v_mul_f32_e64 v42, |v27|, s2
	v_exp_f32_e32 v42, v42
	v_mul_f32_e64 v44, |v11|, s2
	v_exp_f32_e32 v44, v44
	s_or_b64 s[56:57], s[18:19], s[56:57]
	v_add_f32_e32 v42, 1.0, v42
	v_log_f32_e32 v42, v42
	v_add_f32_e32 v44, 1.0, v44
	v_cndmask_b32_e64 v61, 0, -v43, s[56:57]
	v_max_f32_e32 v43, v27, v27
	v_log_f32_e32 v44, v44
	v_max_f32_e32 v43, 0, v43
	v_fmac_f32_e32 v43, 0x3f317218, v42
	v_max_f32_e32 v42, v11, v11
	v_max_f32_e32 v42, 0, v42
	v_fmac_f32_e32 v42, 0x3f317218, v44
	s_or_b64 s[62:63], s[18:19], s[62:63]
	v_cndmask_b32_e64 v64, 0, -v42, s[62:63]
	v_add_u32_e32 v42, 18, v0
	v_cmp_lt_i32_e64 s[64:65], v42, v164
	v_add_u32_e32 v42, 50, v0
	v_cmp_lt_i32_e64 s[66:67], v42, v164
	v_mul_f32_e64 v42, |v28|, s2
	v_exp_f32_e32 v42, v42
	v_mul_f32_e64 v44, |v12|, s2
	v_exp_f32_e32 v44, v44
	s_or_b64 s[60:61], s[18:19], s[60:61]
	v_add_f32_e32 v42, 1.0, v42
	v_log_f32_e32 v42, v42
	v_add_f32_e32 v44, 1.0, v44
	v_cndmask_b32_e64 v63, 0, -v43, s[60:61]
	v_max_f32_e32 v43, v28, v28
	v_log_f32_e32 v44, v44
	v_max_f32_e32 v43, 0, v43
	v_fmac_f32_e32 v43, 0x3f317218, v42
	v_max_f32_e32 v42, v12, v12
	v_max_f32_e32 v42, 0, v42
	v_fmac_f32_e32 v42, 0x3f317218, v44
	s_or_b64 s[66:67], s[18:19], s[66:67]
	v_cndmask_b32_e64 v66, 0, -v42, s[66:67]
	v_add_u32_e32 v42, 19, v0
	v_cmp_lt_i32_e64 s[68:69], v42, v164
	v_add_u32_e32 v42, 51, v0
	v_cmp_lt_i32_e64 s[70:71], v42, v164
	v_mul_f32_e64 v42, |v29|, s2
	v_exp_f32_e32 v42, v42
	v_mul_f32_e64 v44, |v13|, s2
	v_exp_f32_e32 v44, v44
	s_or_b64 s[64:65], s[18:19], s[64:65]
	v_add_f32_e32 v42, 1.0, v42
	v_log_f32_e32 v42, v42
	v_add_f32_e32 v44, 1.0, v44
	v_cndmask_b32_e64 v65, 0, -v43, s[64:65]
	v_max_f32_e32 v43, v29, v29
	v_log_f32_e32 v44, v44
	v_max_f32_e32 v43, 0, v43
	v_fmac_f32_e32 v43, 0x3f317218, v42
	v_max_f32_e32 v42, v13, v13
	v_max_f32_e32 v42, 0, v42
	v_fmac_f32_e32 v42, 0x3f317218, v44
	s_or_b64 s[70:71], s[18:19], s[70:71]
	v_cndmask_b32_e64 v68, 0, -v42, s[70:71]
	v_add_u32_e32 v42, 24, v0
	v_cmp_lt_i32_e64 s[72:73], v42, v164
	v_add_u32_e32 v42, 56, v0
	v_cmp_lt_i32_e64 s[74:75], v42, v164
	v_mul_f32_e64 v42, |v30|, s2
	v_exp_f32_e32 v42, v42
	v_mul_f32_e64 v44, |v14|, s2
	v_exp_f32_e32 v44, v44
	s_or_b64 s[68:69], s[18:19], s[68:69]
	v_add_f32_e32 v42, 1.0, v42
	v_log_f32_e32 v42, v42
	v_add_f32_e32 v44, 1.0, v44
	v_cndmask_b32_e64 v67, 0, -v43, s[68:69]
	v_max_f32_e32 v43, v30, v30
	v_log_f32_e32 v44, v44
	v_max_f32_e32 v43, 0, v43
	v_fmac_f32_e32 v43, 0x3f317218, v42
	v_max_f32_e32 v42, v14, v14
	v_max_f32_e32 v42, 0, v42
	v_fmac_f32_e32 v42, 0x3f317218, v44
	s_or_b64 s[74:75], s[18:19], s[74:75]
	v_cndmask_b32_e64 v70, 0, -v42, s[74:75]
	v_add_u32_e32 v42, 25, v0
	v_cmp_lt_i32_e64 s[76:77], v42, v164
	v_add_u32_e32 v42, 57, v0
	v_cmp_lt_i32_e64 s[78:79], v42, v164
	v_mul_f32_e64 v42, |v31|, s2
	v_exp_f32_e32 v42, v42
	v_mul_f32_e64 v44, |v15|, s2
	v_exp_f32_e32 v44, v44
	s_or_b64 s[72:73], s[18:19], s[72:73]
	v_add_f32_e32 v42, 1.0, v42
	v_log_f32_e32 v42, v42
	v_add_f32_e32 v44, 1.0, v44
	v_cndmask_b32_e64 v69, 0, -v43, s[72:73]
	v_max_f32_e32 v43, v31, v31
	v_log_f32_e32 v44, v44
	v_max_f32_e32 v43, 0, v43
	v_fmac_f32_e32 v43, 0x3f317218, v42
	v_max_f32_e32 v42, v15, v15
	v_max_f32_e32 v42, 0, v42
	v_fmac_f32_e32 v42, 0x3f317218, v44
	s_or_b64 s[78:79], s[18:19], s[78:79]
	v_cndmask_b32_e64 v72, 0, -v42, s[78:79]
	v_add_u32_e32 v42, 26, v0
	v_cmp_lt_i32_e64 s[80:81], v42, v164
	v_add_u32_e32 v42, 58, v0
	v_cmp_lt_i32_e64 s[82:83], v42, v164
	v_mul_f32_e64 v42, |v32|, s2
	v_exp_f32_e32 v42, v42
	v_mul_f32_e64 v44, |v16|, s2
	v_exp_f32_e32 v44, v44
	s_or_b64 s[76:77], s[18:19], s[76:77]
	v_add_f32_e32 v42, 1.0, v42
	v_log_f32_e32 v42, v42
	v_add_f32_e32 v44, 1.0, v44
	v_cndmask_b32_e64 v71, 0, -v43, s[76:77]
	v_max_f32_e32 v43, v32, v32
	v_log_f32_e32 v44, v44
	v_max_f32_e32 v43, 0, v43
	v_fmac_f32_e32 v43, 0x3f317218, v42
	v_max_f32_e32 v42, v16, v16
	v_max_f32_e32 v42, 0, v42
	v_fmac_f32_e32 v42, 0x3f317218, v44
	s_or_b64 s[82:83], s[18:19], s[82:83]
	v_cndmask_b32_e64 v74, 0, -v42, s[82:83]
	v_add_u32_e32 v42, 27, v0
	v_add_u32_e32 v0, 59, v0
	s_mov_b64 s[16:17], s[86:87]
	v_cmp_lt_i32_e64 s[86:87], v0, v164
	v_mul_f32_e64 v0, |v33|, s2
	s_or_b64 s[80:81], s[18:19], s[80:81]
	v_exp_f32_e32 v0, v0
	v_cndmask_b32_e64 v73, 0, -v43, s[80:81]
	v_mul_f32_e64 v43, |v17|, s2
	v_exp_f32_e32 v43, v43
	v_add_f32_e32 v0, 1.0, v0
	v_log_f32_e32 v0, v0
	s_mov_b32 s3, s84
	v_add_f32_e32 v43, 1.0, v43
	v_cmp_lt_i32_e64 s[84:85], v42, v164
	v_max_f32_e32 v42, v33, v33
	v_log_f32_e32 v43, v43
	v_max_f32_e32 v42, 0, v42
	v_fmac_f32_e32 v42, 0x3f317218, v0
	v_max_f32_e32 v0, v17, v17
	v_max_f32_e32 v0, 0, v0
	v_fmac_f32_e32 v0, 0x3f317218, v43
	s_or_b64 s[84:85], s[18:19], s[84:85]
	s_or_b64 s[86:87], s[18:19], s[86:87]
	v_cndmask_b32_e64 v75, 0, -v42, s[84:85]
	v_cndmask_b32_e64 v76, 0, -v0, s[86:87]
	v_add_f32_e32 v0, v34, v35
	v_add_f32_e32 v42, v37, v39
	v_add_f32_e32 v42, v0, v42
	v_add_f32_e32 v0, v36, v38
	v_add_f32_e32 v43, v40, v41
	v_add_f32_e32 v44, v0, v43
	v_add_f32_e32 v0, v51, v56
	v_add_f32_e32 v43, v57, v59
	v_add_f32_e32 v0, v0, v43
	v_add_f32_e32 v43, v53, v55
	v_add_f32_e32 v45, v58, v60
	v_add_f32_e32 v45, v43, v45
	v_add_f32_e32 v43, v61, v63
	v_add_f32_e32 v46, v65, v67
	v_add_f32_e32 v46, v43, v46
	v_add_f32_e32 v43, v62, v64
	v_add_f32_e32 v47, v66, v68
	v_add_f32_e32 v48, v43, v47
	v_add_f32_e32 v43, v69, v71
	v_add_f32_e32 v47, v73, v75
	v_mov_b32_e32 v52, v0
	v_add_f32_e32 v47, v43, v47
	v_add_f32_e32 v43, v70, v72
	v_add_f32_e32 v49, v74, v76
	v_permlane32_swap_b32_e32 v0, v52
	v_add_f32_e32 v49, v43, v49
	v_add_f32_e32 v43, v0, v52
	v_mov_b32_e32 v0, v47
	s_nop 1
	v_permlane32_swap_b32_e32 v47, v0
	v_add_f32_e32 v47, v47, v0
	v_cndmask_b32_e64 v80, 0, v0, s[38:39]
	v_mov_b32_e32 v0, v45
	s_nop 1
	v_permlane32_swap_b32_e32 v45, v0
	v_mov_b32_e32 v84, v49
	v_add_f32_e32 v45, v45, v0
	v_cndmask_b32_e64 v82, 0, v0, s[38:39]
	v_mov_b32_e32 v0, v48
	v_permlane32_swap_b32_e32 v49, v84
	s_nop 0
	v_permlane32_swap_b32_e32 v48, v0
	v_add_f32_e32 v49, v49, v84
	v_cndmask_b32_e64 v83, 0, v0, s[38:39]
	v_pk_add_f32 v[48:49], v[48:49], v[0:1]
	v_mov_b32_e32 v54, v44
	v_add_f32_e32 v0, v83, v49
	v_pk_add_f32 v[48:49], v[48:49], v[48:49] op_sel:[0,1] op_sel_hi:[1,0]
	v_permlane32_swap_b32_e32 v44, v54
	v_add_f32_e32 v49, v82, v48
	v_add_f32_e32 v49, v60, v49
	v_add_f32_e32 v58, v58, v49
	v_add_f32_e32 v60, v55, v58
	v_mov_b32_e32 v55, v48
	v_cndmask_b32_e64 v81, 0, v54, s[38:39]
	v_pk_add_f32 v[44:45], v[44:45], v[54:55]
	v_cndmask_b32_e64 v78, 0, v52, s[38:39]
	v_add_f32_e32 v48, v81, v45
	v_add_f32_e32 v48, v41, v48
	v_mov_b32_e32 v52, v46
	v_add_f32_e32 v54, v40, v48
	v_pk_add_f32 v[40:41], v[44:45], v[44:45] op_sel:[0,1] op_sel_hi:[1,0]
	v_permlane32_swap_b32_e32 v46, v52
	v_add_f32_e32 v0, v68, v0
	v_add_f32_e32 v68, v53, v60
	v_add_f32_e32 v41, v80, v40
	v_mov_b32_e32 v53, v40
	v_cndmask_b32_e64 v79, 0, v52, s[38:39]
	v_add_f32_e32 v44, v75, v41
	v_pk_add_f32 v[40:41], v[46:47], v[52:53]
	v_mov_b32_e32 v50, v42
	v_add_f32_e32 v46, v79, v41
	v_pk_add_f32 v[40:41], v[40:41], v[40:41] op_sel:[0,1] op_sel_hi:[1,0]
	v_add_f32_e32 v46, v67, v46
	v_add_f32_e32 v41, v78, v40
	v_add_f32_e32 v59, v59, v41
	v_add_f32_e32 v47, v65, v46
	v_add_f32_e32 v57, v57, v59
	v_add_f32_e32 v52, v63, v47
	v_add_f32_e32 v56, v56, v57
	v_permlane32_swap_b32_e32 v42, v50
	v_add_f32_e32 v53, v61, v52
	v_add_f32_e32 v61, v51, v56
	v_mov_b32_e32 v51, v40
	v_cndmask_b32_e64 v77, 0, v50, s[38:39]
	v_pk_add_f32 v[40:41], v[42:43], v[50:51]
	v_add_f32_e32 v38, v38, v54
	v_add_f32_e32 v42, v77, v41
	v_add_f32_e32 v39, v39, v42
	v_add_f32_e32 v37, v37, v39
	v_add_f32_e32 v36, v36, v38
	v_add_f32_e32 v35, v35, v37
	v_add_f32_e32 v2, v2, v36
	v_add_f32_e32 v19, v19, v35
	v_add_f32_e32 v3, v3, v38
	v_mul_f32_e32 v2, 0x3fb8aa3b, v2
	v_mul_f32_e32 v19, 0x3fb8aa3b, v19
	v_mul_f32_e32 v3, 0x3fb8aa3b, v3
	v_exp_f32_e32 v2, v2
	v_exp_f32_e32 v19, v19
	v_exp_f32_e32 v3, v3
	v_add_f32_e32 v34, v34, v35
	v_add_f32_e32 v18, v18, v34
	v_cndmask_b32_e64 v34, 0, v2, s[0:1]
	v_cndmask_b32_e64 v2, 0, v19, s[14:15]
	v_cndmask_b32_e64 v19, 0, v3, s[4:5]
	v_add_f32_e32 v3, v20, v37
	v_add_f32_e32 v4, v4, v54
	v_add_f32_e32 v20, v21, v39
	v_add_f32_e32 v5, v5, v48
	v_mul_f32_e32 v4, 0x3fb8aa3b, v4
	v_mul_f32_e32 v20, 0x3fb8aa3b, v20
	v_mul_f32_e32 v5, 0x3fb8aa3b, v5
	v_exp_f32_e32 v4, v4
	v_exp_f32_e32 v20, v20
	v_exp_f32_e32 v5, v5
	v_add_f32_e32 v6, v6, v68
	v_cndmask_b32_e64 v21, 0, v4, s[8:9]
	v_cndmask_b32_e64 v4, 0, v20, s[10:11]
	v_cndmask_b32_e64 v20, 0, v5, s[12:13]
	v_add_f32_e32 v5, v22, v61
	v_add_f32_e32 v22, v23, v56
	v_add_f32_e32 v7, v7, v60
	v_mul_f32_e32 v6, 0x3fb8aa3b, v6
	v_mul_f32_e32 v22, 0x3fb8aa3b, v22
	v_mul_f32_e32 v7, 0x3fb8aa3b, v7
	v_exp_f32_e32 v6, v6
	v_exp_f32_e32 v22, v22
	v_exp_f32_e32 v7, v7
	v_add_f32_e32 v8, v8, v58
	v_cndmask_b32_e64 v23, 0, v6, s[42:43]
	v_cndmask_b32_e64 v6, 0, v22, s[44:45]
	v_cndmask_b32_e64 v22, 0, v7, s[46:47]
	v_add_f32_e32 v7, v24, v57
	v_add_f32_e32 v24, v25, v59
	v_add_f32_e32 v9, v9, v49
	v_mul_f32_e32 v8, 0x3fb8aa3b, v8
	v_mul_f32_e32 v24, 0x3fb8aa3b, v24
	v_mul_f32_e32 v9, 0x3fb8aa3b, v9
	v_exp_f32_e32 v8, v8
	v_exp_f32_e32 v24, v24
	v_exp_f32_e32 v9, v9
	v_add_f32_e32 v66, v66, v0
	v_add_f32_e32 v64, v64, v66
	v_add_f32_e32 v62, v62, v64
	v_cndmask_b32_e64 v25, 0, v8, s[50:51]
	v_cndmask_b32_e64 v8, 0, v24, s[52:53]
	v_cndmask_b32_e64 v24, 0, v9, s[54:55]
	v_add_f32_e32 v9, v26, v53
	v_add_f32_e32 v10, v10, v62
	v_add_f32_e32 v26, v27, v52
	v_add_f32_e32 v11, v11, v64
	v_mul_f32_e32 v10, 0x3fb8aa3b, v10
	v_mul_f32_e32 v26, 0x3fb8aa3b, v26
	v_mul_f32_e32 v11, 0x3fb8aa3b, v11
	v_exp_f32_e32 v10, v10
	v_exp_f32_e32 v26, v26
	v_exp_f32_e32 v11, v11
	v_add_f32_e32 v84, 0, v84
	v_cndmask_b32_e64 v27, 0, v10, s[58:59]
	v_cndmask_b32_e64 v10, 0, v26, s[60:61]
	v_cndmask_b32_e64 v26, 0, v11, s[62:63]
	v_add_f32_e32 v11, v28, v47
	v_add_f32_e32 v12, v12, v66
	v_add_f32_e32 v28, v29, v46
	v_cndmask_b32_e64 v84, 0, v84, s[38:39]
	v_mul_f32_e32 v12, 0x3fb8aa3b, v12
	v_mul_f32_e32 v28, 0x3fb8aa3b, v28
	v_add_f32_e32 v76, v76, v84
	v_add_f32_e32 v45, v73, v44
	v_exp_f32_e32 v12, v12
	v_exp_f32_e32 v28, v28
	v_add_f32_e32 v74, v74, v76
	v_add_f32_e32 v55, v71, v45
	v_add_f32_e32 v72, v72, v74
	v_add_f32_e32 v69, v69, v55
	v_add_f32_e32 v70, v70, v72
	v_add_f32_e32 v0, v13, v0
	v_add_f32_e32 v13, v30, v69
	v_mul_f32_e32 v3, 0x3fb8aa3b, v3
	v_mul_f32_e32 v5, 0x3fb8aa3b, v5
	v_mul_f32_e32 v7, 0x3fb8aa3b, v7
	v_mul_f32_e32 v9, 0x3fb8aa3b, v9
	v_mul_f32_e32 v11, 0x3fb8aa3b, v11
	v_cndmask_b32_e64 v29, 0, v12, s[66:67]
	v_cndmask_b32_e64 v12, 0, v28, s[68:69]
	v_mul_f32_e32 v13, 0x3fb8aa3b, v13
	v_add_f32_e32 v14, v14, v70
	v_add_f32_e32 v28, v31, v55
	v_add_f32_e32 v15, v15, v72
	v_add_f32_e32 v30, v32, v45
	v_add_f32_e32 v16, v16, v74
	v_add_f32_e32 v31, v33, v44
	v_add_f32_e32 v17, v17, v76
	v_mul_f32_e32 v18, 0x3fb8aa3b, v18
	v_exp_f32_e32 v3, v3
	v_exp_f32_e32 v5, v5
	v_exp_f32_e32 v7, v7
	v_exp_f32_e32 v9, v9
	v_exp_f32_e32 v11, v11
	v_mul_f32_e32 v0, 0x3fb8aa3b, v0
	v_exp_f32_e32 v13, v13
	v_mul_f32_e32 v14, 0x3fb8aa3b, v14
	v_mul_f32_e32 v28, 0x3fb8aa3b, v28
	v_mul_f32_e32 v15, 0x3fb8aa3b, v15
	v_mul_f32_e32 v30, 0x3fb8aa3b, v30
	v_mul_f32_e32 v16, 0x3fb8aa3b, v16
	v_mul_f32_e32 v31, 0x3fb8aa3b, v31
	v_mul_f32_e32 v17, 0x3fb8aa3b, v17
	v_exp_f32_e32 v18, v18
	v_exp_f32_e32 v0, v0
	v_exp_f32_e32 v14, v14
	v_exp_f32_e32 v28, v28
	v_exp_f32_e32 v15, v15
	v_exp_f32_e32 v30, v30
	v_exp_f32_e32 v16, v16
	v_exp_f32_e32 v31, v31
	v_exp_f32_e32 v17, v17
	v_cndmask_b32_e64 v3, 0, v3, s[6:7]
	v_cndmask_b32_e64 v5, 0, v5, s[40:41]
	v_cndmask_b32_e64 v7, 0, v7, s[48:49]
	v_cndmask_b32_e64 v9, 0, v9, s[56:57]
	v_cndmask_b32_e64 v11, 0, v11, s[64:65]
	v_cndmask_b32_e64 v13, 0, v13, s[72:73]
	v_readlane_b32 s46, v255, 18
	v_readlane_b32 s44, v255, 16
	v_readlane_b32 s52, v255, 10
	v_cndmask_b32_e32 v18, 0, v18, vcc
	v_readlane_b32 s57, v255, 15
	v_readlane_b32 s56, v255, 14
	v_cndmask_b32_e64 v0, 0, v0, s[70:71]
	v_cndmask_b32_e64 v14, 0, v14, s[74:75]
	v_cndmask_b32_e64 v28, 0, v28, s[76:77]
	v_cndmask_b32_e64 v15, 0, v15, s[78:79]
	v_cndmask_b32_e64 v30, 0, v30, s[80:81]
	v_cndmask_b32_e64 v16, 0, v16, s[82:83]
	v_cndmask_b32_e64 v31, 0, v31, s[84:85]
	s_mov_b32 s84, s3
	v_cndmask_b32_e64 v17, 0, v17, s[86:87]
	s_mov_b64 s[86:87], s[16:17]
	v_readlane_b32 s17, v255, 39
	v_readlane_b32 s16, v255, 20
	v_readlane_b32 s47, v255, 19
	v_readlane_b32 s45, v255, 17
	v_readlane_b32 s55, v255, 13
	v_readlane_b32 s54, v255, 12
	v_readlane_b32 s53, v255, 11
	v_add_f32_e32 v153, v40, v41
	v_cvt_pk_bf16_f32 v2, v18, v2
	v_cvt_pk_bf16_f32 v3, v3, v4
	v_cvt_pk_bf16_f32 v4, v5, v6
	v_cvt_pk_bf16_f32 v5, v7, v8
	v_cvt_pk_bf16_f32 v6, v9, v10
	v_cvt_pk_bf16_f32 v7, v11, v12
	v_cvt_pk_bf16_f32 v8, v13, v28
	v_cvt_pk_bf16_f32 v9, v30, v31
	v_cvt_pk_bf16_f32 v10, v34, v19
	v_cvt_pk_bf16_f32 v11, v21, v20
	v_cvt_pk_bf16_f32 v12, v23, v22
	v_cvt_pk_bf16_f32 v13, v25, v24
	v_cvt_pk_bf16_f32 v80, v27, v26
	v_cvt_pk_bf16_f32 v81, v29, v0
	v_cvt_pk_bf16_f32 v82, v14, v15
	v_cvt_pk_bf16_f32 v83, v16, v17
	s_nop 0
	s_setprio 1
	ds_read_b64_tr_b16 v[14:15], v159 offset:0x0
	ds_read_b64_tr_b16 v[16:17], v159 offset:0x100
	ds_read_b64_tr_b16 v[32:33], v159 offset:0x1000
	ds_read_b64_tr_b16 v[34:35], v159 offset:0x1100
	ds_read_b64_tr_b16 v[36:37], v159 offset:0x2000
	ds_read_b64_tr_b16 v[38:39], v159 offset:0x2100
	ds_read_b64_tr_b16 v[40:41], v159 offset:0x3000
	ds_read_b64_tr_b16 v[42:43], v159 offset:0x3100
	s_waitcnt lgkmcnt(0)
	s_nop 0
	v_mfma_f32_32x32x16_bf16 v[16:31], v[2:5], v[14:17], 0
	v_mfma_f32_32x32x16_bf16 v[16:31], v[6:9], v[32:35], v[16:31]
	ds_read_b64_tr_b16 v[32:33], v159 offset:0x200
	ds_read_b64_tr_b16 v[34:35], v159 offset:0x300
	ds_read_b64_tr_b16 v[48:49], v159 offset:0x1200
	ds_read_b64_tr_b16 v[50:51], v159 offset:0x1300
	ds_read_b64_tr_b16 v[52:53], v159 offset:0x2200
	ds_read_b64_tr_b16 v[54:55], v159 offset:0x2300
	ds_read_b64_tr_b16 v[56:57], v159 offset:0x3200
	v_mfma_f32_32x32x16_bf16 v[16:31], v[10:13], v[36:39], v[16:31]
	ds_read_b64_tr_b16 v[58:59], v159 offset:0x3300
	s_waitcnt lgkmcnt(0)
	v_mfma_f32_32x32x16_bf16 v[16:31], v[80:83], v[40:43], v[16:31]
	v_mfma_f32_32x32x16_bf16 v[32:47], v[2:5], v[32:35], 0
	v_mfma_f32_32x32x16_bf16 v[32:47], v[6:9], v[48:51], v[32:47]
	ds_read_b64_tr_b16 v[48:49], v159 offset:0x400
	ds_read_b64_tr_b16 v[50:51], v159 offset:0x500
	ds_read_b64_tr_b16 v[64:65], v159 offset:0x1400
	ds_read_b64_tr_b16 v[66:67], v159 offset:0x1500
	ds_read_b64_tr_b16 v[68:69], v159 offset:0x2400
	ds_read_b64_tr_b16 v[70:71], v159 offset:0x2500
	ds_read_b64_tr_b16 v[72:73], v159 offset:0x3400
	v_mfma_f32_32x32x16_bf16 v[32:47], v[10:13], v[52:55], v[32:47]
	ds_read_b64_tr_b16 v[74:75], v159 offset:0x3500
	s_waitcnt lgkmcnt(0)
	v_mfma_f32_32x32x16_bf16 v[32:47], v[80:83], v[56:59], v[32:47]
	v_mfma_f32_32x32x16_bf16 v[48:63], v[2:5], v[48:51], 0
	v_mfma_f32_32x32x16_bf16 v[48:63], v[6:9], v[64:67], v[48:63]
	ds_read_b64_tr_b16 v[64:65], v159 offset:0x600
	ds_read_b64_tr_b16 v[66:67], v159 offset:0x700
	ds_read_b64_tr_b16 v[84:85], v159 offset:0x1600
	ds_read_b64_tr_b16 v[86:87], v159 offset:0x1700
	ds_read_b64_tr_b16 v[88:89], v159 offset:0x2600
	ds_read_b64_tr_b16 v[90:91], v159 offset:0x2700
	ds_read_b64_tr_b16 v[92:93], v159 offset:0x3600
	v_mfma_f32_32x32x16_bf16 v[48:63], v[10:13], v[68:71], v[48:63]
	ds_read_b64_tr_b16 v[94:95], v159 offset:0x3700
	s_waitcnt lgkmcnt(0)
	v_mfma_f32_32x32x16_bf16 v[48:63], v[80:83], v[72:75], v[48:63]
	v_mfma_f32_32x32x16_bf16 v[64:79], v[2:5], v[64:67], 0
	v_mfma_f32_32x32x16_bf16 v[64:79], v[6:9], v[84:87], v[64:79]
	v_mfma_f32_32x32x16_bf16 v[64:79], v[10:13], v[88:91], v[64:79]
	v_mfma_f32_32x32x16_bf16 v[64:79], v[80:83], v[92:95], v[64:79]
	s_setprio 0
	s_branch .LBB0_1092

.LBB0_1107:
	s_add_i32 s0, s20, 0x80
	s_cmp_ge_i32 s0, s36
	s_cselect_b64 s[0:1], -1, 0
	s_or_b64 s[0:1], s[0:1], s[18:19]
	s_and_b64 vcc, exec, s[0:1]
	s_cbranch_vccnz .LBB0_1109
	s_add_i32 s0, s20, 0xbf
	s_cmp_lt_i32 s0, s27
	s_mul_i32 s0, s93, 0xa100
	s_mov_b32 s35, s36
	s_mov_b32 s36, s27
	s_cselect_b64 s[26:27], -1, 0
	s_add_i32 s0, s0, 0
	v_add_u32_e32 v0, s0, v160
	ds_read_b128 v[2:5], v0
	ds_read_b128 v[6:9], v0 offset:8192
	v_add_u32_e32 v0, s0, v161
	ds_read_b128 v[10:13], v0
	ds_read_b128 v[170:173], v0 offset:8192
	s_setprio 1
	v_add_u32_e32 v0, s0, v162
	ds_read_b128 v[174:177], v0
	ds_read_b128 v[178:181], v0 offset:8192
	v_add_u32_e32 v0, s0, v163
	ds_read_b128 v[182:185], v0
	ds_read_b128 v[186:189], v0 offset:8192
	s_waitcnt lgkmcnt(7)
	v_mfma_f32_32x32x16_bf16 v[96:111], v[2:5], v[112:115], 0
	s_waitcnt lgkmcnt(6)
	v_mfma_f32_32x32x16_bf16 v[80:95], v[6:9], v[112:115], 0
	s_waitcnt lgkmcnt(5)
	v_mfma_f32_32x32x16_bf16 v[96:111], v[10:13], v[116:119], v[96:111]
	s_waitcnt lgkmcnt(4)
	v_mfma_f32_32x32x16_bf16 v[80:95], v[170:173], v[116:119], v[80:95]
	v_add_u32_e32 v0, s0, v165
	ds_read_b128 v[2:5], v0 offset:8192
	ds_read_b128 v[6:9], v0
	v_add_u32_e32 v0, s0, v166
	ds_read_b128 v[10:13], v0 offset:8192
	ds_read_b128 v[170:173], v0
	s_waitcnt lgkmcnt(7)
	v_mfma_f32_32x32x16_bf16 v[96:111], v[174:177], v[120:123], v[96:111]
	s_waitcnt lgkmcnt(6)
	v_mfma_f32_32x32x16_bf16 v[80:95], v[178:181], v[120:123], v[80:95]
	s_waitcnt lgkmcnt(5)
	v_mfma_f32_32x32x16_bf16 v[96:111], v[182:185], v[124:127], v[96:111]
	s_waitcnt lgkmcnt(4)
	v_mfma_f32_32x32x16_bf16 v[80:95], v[186:189], v[124:127], v[80:95]
	v_add_u32_e32 v0, s0, v167
	ds_read_b128 v[174:177], v0
	ds_read_b128 v[178:181], v0 offset:8192
	v_add_u32_e32 v0, s0, v168
	ds_read_b128 v[182:185], v0
	ds_read_b128 v[186:189], v0 offset:8192
	s_waitcnt lgkmcnt(4)
	v_mfma_f32_32x32x16_bf16 v[96:111], v[170:173], v[128:131], v[96:111]
	v_mfma_f32_32x32x16_bf16 v[80:95], v[10:13], v[128:131], v[80:95]
	v_mfma_f32_32x32x16_bf16 v[96:111], v[6:9], v[132:135], v[96:111]
	v_mfma_f32_32x32x16_bf16 v[80:95], v[2:5], v[132:135], v[80:95]
	s_waitcnt lgkmcnt(3)
	v_mfma_f32_32x32x16_bf16 v[96:111], v[174:177], v[136:139], v[96:111]
	s_waitcnt lgkmcnt(2)
	v_mfma_f32_32x32x16_bf16 v[80:95], v[178:181], v[136:139], v[80:95]
	s_waitcnt lgkmcnt(1)
	v_mfma_f32_32x32x16_bf16 v[96:111], v[182:185], v[140:143], v[96:111]
	s_waitcnt lgkmcnt(0)
	v_mfma_f32_32x32x16_bf16 v[80:95], v[186:189], v[140:143], v[80:95]
	s_setprio 0
	v_add_u32_e32 v8, s20, v158
	v_add_u32_e32 v0, 0x80, v8
	v_cmp_lt_i32_e32 vcc, v0, v164
	v_add_u32_e32 v0, 0xa0, v8
	s_mov_b32 s3, 0xbfb8aa3b
	v_cmp_lt_i32_e64 s[0:1], v0, v164
	s_nop 2
	v_mul_f32_e64 v0, |v96|, s3
	v_exp_f32_e32 v0, v0
	v_max_f32_e32 v2, v96, v96
	v_max_f32_e32 v2, 0, v2
	v_mul_f32_e64 v3, |v80|, s3
	v_add_f32_e32 v0, 1.0, v0
	v_log_f32_e32 v0, v0
	s_or_b64 vcc, s[26:27], vcc
	v_exp_f32_e32 v3, v3
	s_mov_b32 s2, s7
	v_fmac_f32_e32 v2, 0x3f317218, v0
	v_max_f32_e32 v0, v80, v80
	v_max_f32_e32 v4, 0, v0
	v_cndmask_b32_e64 v0, 0, -v2, vcc
	v_add_u32_e32 v2, 0x81, v8
	v_cmp_lt_i32_e64 s[4:5], v2, v164
	v_add_u32_e32 v2, 0xa1, v8
	v_cmp_lt_i32_e64 s[6:7], v2, v164
	v_mul_f32_e64 v2, |v97|, s3
	v_exp_f32_e32 v2, v2
	v_add_f32_e32 v3, 1.0, v3
	v_log_f32_e32 v3, v3
	s_or_b64 s[0:1], s[26:27], s[0:1]
	v_add_f32_e32 v2, 1.0, v2
	v_log_f32_e32 v2, v2
	v_fmac_f32_e32 v4, 0x3f317218, v3
	v_cndmask_b32_e64 v3, 0, -v4, s[0:1]
	v_max_f32_e32 v4, v97, v97
	v_max_f32_e32 v4, 0, v4
	v_mul_f32_e64 v5, |v81|, s3
	v_fmac_f32_e32 v4, 0x3f317218, v2
	v_max_f32_e32 v2, v81, v81
	s_or_b64 s[14:15], s[26:27], s[4:5]
	v_exp_f32_e32 v5, v5
	v_max_f32_e32 v6, 0, v2
	v_cndmask_b32_e64 v2, 0, -v4, s[14:15]
	v_add_u32_e32 v4, 0x82, v8
	s_or_b64 s[4:5], s[26:27], s[6:7]
	v_cmp_lt_i32_e64 s[6:7], v4, v164
	v_add_u32_e32 v4, 0xa2, v8
	v_cmp_lt_i32_e64 s[8:9], v4, v164
	v_mul_f32_e64 v4, |v98|, s3
	v_exp_f32_e32 v4, v4
	v_add_f32_e32 v5, 1.0, v5
	v_log_f32_e32 v5, v5
	v_mul_f32_e64 v7, |v82|, s3
	v_add_f32_e32 v4, 1.0, v4
	v_log_f32_e32 v4, v4
	v_fmac_f32_e32 v6, 0x3f317218, v5
	v_cndmask_b32_e64 v5, 0, -v6, s[4:5]
	v_max_f32_e32 v6, v98, v98
	v_max_f32_e32 v6, 0, v6
	v_fmac_f32_e32 v6, 0x3f317218, v4
	v_max_f32_e32 v4, v82, v82
	s_or_b64 s[6:7], s[26:27], s[6:7]
	v_exp_f32_e32 v7, v7
	v_max_f32_e32 v9, 0, v4
	v_cndmask_b32_e64 v4, 0, -v6, s[6:7]
	v_add_u32_e32 v6, 0x83, v8
	v_cmp_lt_i32_e64 s[10:11], v6, v164
	v_add_u32_e32 v6, 0xa3, v8
	v_cmp_lt_i32_e64 s[12:13], v6, v164
	v_mul_f32_e64 v6, |v99|, s3
	v_exp_f32_e32 v6, v6
	v_add_f32_e32 v7, 1.0, v7
	v_log_f32_e32 v7, v7
	v_mul_f32_e64 v10, |v83|, s3
	v_exp_f32_e32 v10, v10
	v_add_f32_e32 v6, 1.0, v6
	v_log_f32_e32 v6, v6
	v_fmac_f32_e32 v9, 0x3f317218, v7
	s_or_b64 s[8:9], s[26:27], s[8:9]
	v_cndmask_b32_e64 v7, 0, -v9, s[8:9]
	v_max_f32_e32 v9, v99, v99
	v_max_f32_e32 v9, 0, v9
	v_add_f32_e32 v10, 1.0, v10
	v_log_f32_e32 v10, v10
	v_fmac_f32_e32 v9, 0x3f317218, v6
	v_max_f32_e32 v6, v83, v83
	s_or_b64 s[10:11], s[26:27], s[10:11]
	v_max_f32_e32 v11, 0, v6
	v_cndmask_b32_e64 v6, 0, -v9, s[10:11]
	v_add_u32_e32 v9, 0x88, v8
	v_cmp_lt_i32_e64 s[42:43], v9, v164
	v_add_u32_e32 v9, 0xa8, v8
	v_cmp_lt_i32_e64 s[44:45], v9, v164
	v_mul_f32_e64 v9, |v100|, s3
	v_fmac_f32_e32 v11, 0x3f317218, v10
	s_or_b64 s[12:13], s[26:27], s[12:13]
	v_exp_f32_e32 v9, v9
	v_cndmask_b32_e64 v15, 0, -v11, s[12:13]
	v_mul_f32_e64 v11, |v84|, s3
	v_exp_f32_e32 v11, v11
	v_add_f32_e32 v9, 1.0, v9
	v_log_f32_e32 v9, v9
	v_max_f32_e32 v10, v100, v100
	v_add_f32_e32 v11, 1.0, v11
	v_log_f32_e32 v11, v11
	v_max_f32_e32 v10, 0, v10
	v_fmac_f32_e32 v10, 0x3f317218, v9
	v_max_f32_e32 v9, v84, v84
	v_max_f32_e32 v9, 0, v9
	v_fmac_f32_e32 v9, 0x3f317218, v11
	s_or_b64 s[44:45], s[26:27], s[44:45]
	v_cndmask_b32_e64 v171, 0, -v9, s[44:45]
	v_add_u32_e32 v9, 0x89, v8
	v_cmp_lt_i32_e64 s[46:47], v9, v164
	v_add_u32_e32 v9, 0xa9, v8
	v_cmp_lt_i32_e64 s[48:49], v9, v164
	v_mul_f32_e64 v9, |v101|, s3
	v_exp_f32_e32 v9, v9
	v_mul_f32_e64 v11, |v85|, s3
	v_exp_f32_e32 v11, v11
	s_or_b64 s[42:43], s[26:27], s[42:43]
	v_add_f32_e32 v9, 1.0, v9
	v_log_f32_e32 v9, v9
	v_add_f32_e32 v11, 1.0, v11
	v_cndmask_b32_e64 v169, 0, -v10, s[42:43]
	v_max_f32_e32 v10, v101, v101
	v_log_f32_e32 v11, v11
	v_max_f32_e32 v10, 0, v10
	v_fmac_f32_e32 v10, 0x3f317218, v9
	v_max_f32_e32 v9, v85, v85
	v_max_f32_e32 v9, 0, v9
	v_fmac_f32_e32 v9, 0x3f317218, v11
	s_or_b64 s[48:49], s[26:27], s[48:49]
	v_cndmask_b32_e64 v173, 0, -v9, s[48:49]
	v_add_u32_e32 v9, 0x8a, v8
	v_cmp_lt_i32_e64 s[50:51], v9, v164
	v_add_u32_e32 v9, 0xaa, v8
	v_cmp_lt_i32_e64 s[52:53], v9, v164
	v_mul_f32_e64 v9, |v102|, s3
	v_exp_f32_e32 v9, v9
	v_mul_f32_e64 v11, |v86|, s3
	v_exp_f32_e32 v11, v11
	s_or_b64 s[46:47], s[26:27], s[46:47]
	v_add_f32_e32 v9, 1.0, v9
	v_log_f32_e32 v9, v9
	v_add_f32_e32 v11, 1.0, v11
	v_cndmask_b32_e64 v176, 0, -v10, s[46:47]
	v_max_f32_e32 v10, v102, v102
	v_log_f32_e32 v11, v11
	v_max_f32_e32 v10, 0, v10
	v_fmac_f32_e32 v10, 0x3f317218, v9
	v_max_f32_e32 v9, v86, v86
	v_max_f32_e32 v9, 0, v9
	v_fmac_f32_e32 v9, 0x3f317218, v11
	s_or_b64 s[52:53], s[26:27], s[52:53]
	v_cndmask_b32_e64 v178, 0, -v9, s[52:53]
	v_add_u32_e32 v9, 0x8b, v8
	v_cmp_lt_i32_e64 s[54:55], v9, v164
	v_add_u32_e32 v9, 0xab, v8
	v_cmp_lt_i32_e64 s[56:57], v9, v164
	v_mul_f32_e64 v9, |v103|, s3
	v_exp_f32_e32 v9, v9
	v_mul_f32_e64 v11, |v87|, s3
	v_exp_f32_e32 v11, v11
	s_or_b64 s[50:51], s[26:27], s[50:51]
	v_add_f32_e32 v9, 1.0, v9
	v_log_f32_e32 v9, v9
	v_add_f32_e32 v11, 1.0, v11
	v_cndmask_b32_e64 v177, 0, -v10, s[50:51]
	v_max_f32_e32 v10, v103, v103
	v_log_f32_e32 v11, v11
	v_max_f32_e32 v10, 0, v10
	v_fmac_f32_e32 v10, 0x3f317218, v9
	v_max_f32_e32 v9, v87, v87
	v_max_f32_e32 v9, 0, v9
	v_fmac_f32_e32 v9, 0x3f317218, v11
	s_or_b64 s[56:57], s[26:27], s[56:57]
	v_cndmask_b32_e64 v180, 0, -v9, s[56:57]
	v_add_u32_e32 v9, 0x90, v8
	v_cmp_lt_i32_e64 s[58:59], v9, v164
	v_add_u32_e32 v9, 0xb0, v8
	v_cmp_lt_i32_e64 s[60:61], v9, v164
	v_mul_f32_e64 v9, |v104|, s3
	v_exp_f32_e32 v9, v9
	v_mul_f32_e64 v11, |v88|, s3
	v_exp_f32_e32 v11, v11
	s_or_b64 s[54:55], s[26:27], s[54:55]
	v_add_f32_e32 v9, 1.0, v9
	v_log_f32_e32 v9, v9
	v_add_f32_e32 v11, 1.0, v11
	v_cndmask_b32_e64 v179, 0, -v10, s[54:55]
	v_max_f32_e32 v10, v104, v104
	v_log_f32_e32 v11, v11
	v_max_f32_e32 v10, 0, v10
	v_fmac_f32_e32 v10, 0x3f317218, v9
	v_max_f32_e32 v9, v88, v88
	v_max_f32_e32 v9, 0, v9
	v_fmac_f32_e32 v9, 0x3f317218, v11
	s_or_b64 s[60:61], s[26:27], s[60:61]
	v_cndmask_b32_e64 v182, 0, -v9, s[60:61]
	v_add_u32_e32 v9, 0x91, v8
	v_cmp_lt_i32_e64 s[62:63], v9, v164
	v_add_u32_e32 v9, 0xb1, v8
	v_cmp_lt_i32_e64 s[64:65], v9, v164
	v_mul_f32_e64 v9, |v105|, s3
	v_exp_f32_e32 v9, v9
	v_mul_f32_e64 v11, |v89|, s3
	v_exp_f32_e32 v11, v11
	s_or_b64 s[58:59], s[26:27], s[58:59]
	v_add_f32_e32 v9, 1.0, v9
	v_log_f32_e32 v9, v9
	v_add_f32_e32 v11, 1.0, v11
	v_cndmask_b32_e64 v181, 0, -v10, s[58:59]
	v_max_f32_e32 v10, v105, v105
	v_log_f32_e32 v11, v11
	v_max_f32_e32 v10, 0, v10
	v_fmac_f32_e32 v10, 0x3f317218, v9
	v_max_f32_e32 v9, v89, v89
	v_max_f32_e32 v9, 0, v9
	v_fmac_f32_e32 v9, 0x3f317218, v11
	s_or_b64 s[64:65], s[26:27], s[64:65]
	v_cndmask_b32_e64 v184, 0, -v9, s[64:65]
	v_add_u32_e32 v9, 0x92, v8
	v_cmp_lt_i32_e64 s[66:67], v9, v164
	v_add_u32_e32 v9, 0xb2, v8
	v_cmp_lt_i32_e64 s[68:69], v9, v164
	v_mul_f32_e64 v9, |v106|, s3
	v_exp_f32_e32 v9, v9
	v_mul_f32_e64 v11, |v90|, s3
	v_exp_f32_e32 v11, v11
	s_or_b64 s[62:63], s[26:27], s[62:63]
	v_add_f32_e32 v9, 1.0, v9
	v_log_f32_e32 v9, v9
	v_add_f32_e32 v11, 1.0, v11
	v_cndmask_b32_e64 v183, 0, -v10, s[62:63]
	v_max_f32_e32 v10, v106, v106
	v_log_f32_e32 v11, v11
	v_max_f32_e32 v10, 0, v10
	v_fmac_f32_e32 v10, 0x3f317218, v9
	v_max_f32_e32 v9, v90, v90
	v_max_f32_e32 v9, 0, v9
	v_fmac_f32_e32 v9, 0x3f317218, v11
	s_or_b64 s[68:69], s[26:27], s[68:69]
	v_cndmask_b32_e64 v186, 0, -v9, s[68:69]
	v_add_u32_e32 v9, 0x93, v8
	v_cmp_lt_i32_e64 s[70:71], v9, v164
	v_add_u32_e32 v9, 0xb3, v8
	v_cmp_lt_i32_e64 s[72:73], v9, v164
	v_mul_f32_e64 v9, |v107|, s3
	v_exp_f32_e32 v9, v9
	v_mul_f32_e64 v11, |v91|, s3
	v_exp_f32_e32 v11, v11
	s_or_b64 s[66:67], s[26:27], s[66:67]
	v_add_f32_e32 v9, 1.0, v9
	v_log_f32_e32 v9, v9
	v_add_f32_e32 v11, 1.0, v11
	v_cndmask_b32_e64 v185, 0, -v10, s[66:67]
	v_max_f32_e32 v10, v107, v107
	v_log_f32_e32 v11, v11
	v_max_f32_e32 v10, 0, v10
	v_fmac_f32_e32 v10, 0x3f317218, v9
	v_max_f32_e32 v9, v91, v91
	v_max_f32_e32 v9, 0, v9
	v_fmac_f32_e32 v9, 0x3f317218, v11
	s_or_b64 s[72:73], s[26:27], s[72:73]
	v_cndmask_b32_e64 v188, 0, -v9, s[72:73]
	v_add_u32_e32 v9, 0x98, v8
	v_cmp_lt_i32_e64 s[74:75], v9, v164
	v_add_u32_e32 v9, 0xb8, v8
	v_cmp_lt_i32_e64 s[76:77], v9, v164
	v_mul_f32_e64 v9, |v108|, s3
	v_exp_f32_e32 v9, v9
	v_mul_f32_e64 v11, |v92|, s3
	v_exp_f32_e32 v11, v11
	s_or_b64 s[70:71], s[26:27], s[70:71]
	v_add_f32_e32 v9, 1.0, v9
	v_log_f32_e32 v9, v9
	v_add_f32_e32 v11, 1.0, v11
	v_cndmask_b32_e64 v187, 0, -v10, s[70:71]
	v_max_f32_e32 v10, v108, v108
	v_log_f32_e32 v11, v11
	v_max_f32_e32 v10, 0, v10
	v_fmac_f32_e32 v10, 0x3f317218, v9
	v_max_f32_e32 v9, v92, v92
	v_max_f32_e32 v9, 0, v9
	v_fmac_f32_e32 v9, 0x3f317218, v11
	s_or_b64 s[76:77], s[26:27], s[76:77]
	v_cndmask_b32_e64 v190, 0, -v9, s[76:77]
	v_add_u32_e32 v9, 0x99, v8
	v_cmp_lt_i32_e64 s[78:79], v9, v164
	v_add_u32_e32 v9, 0xb9, v8
	v_cmp_lt_i32_e64 s[80:81], v9, v164
	v_mul_f32_e64 v9, |v109|, s3
	v_exp_f32_e32 v9, v9
	v_mul_f32_e64 v11, |v93|, s3
	v_exp_f32_e32 v11, v11
	s_or_b64 s[74:75], s[26:27], s[74:75]
	v_add_f32_e32 v9, 1.0, v9
	v_log_f32_e32 v9, v9
	v_add_f32_e32 v11, 1.0, v11
	v_cndmask_b32_e64 v189, 0, -v10, s[74:75]
	v_max_f32_e32 v10, v109, v109
	v_log_f32_e32 v11, v11
	v_max_f32_e32 v10, 0, v10
	v_fmac_f32_e32 v10, 0x3f317218, v9
	v_max_f32_e32 v9, v93, v93
	v_max_f32_e32 v9, 0, v9
	v_fmac_f32_e32 v9, 0x3f317218, v11
	s_or_b64 s[80:81], s[26:27], s[80:81]
	v_cndmask_b32_e64 v192, 0, -v9, s[80:81]
	v_add_u32_e32 v9, 0x9a, v8
	v_cmp_lt_i32_e64 s[82:83], v9, v164
	v_add_u32_e32 v9, 0xba, v8
	s_mov_b32 s21, s84
	v_cmp_lt_i32_e64 s[84:85], v9, v164
	v_mul_f32_e64 v9, |v110|, s3
	v_exp_f32_e32 v9, v9
	v_mul_f32_e64 v11, |v94|, s3
	v_exp_f32_e32 v11, v11
	s_or_b64 s[78:79], s[26:27], s[78:79]
	v_add_f32_e32 v9, 1.0, v9
	v_log_f32_e32 v9, v9
	v_add_f32_e32 v11, 1.0, v11
	v_cndmask_b32_e64 v191, 0, -v10, s[78:79]
	v_max_f32_e32 v10, v110, v110
	v_log_f32_e32 v11, v11
	v_max_f32_e32 v10, 0, v10
	v_fmac_f32_e32 v10, 0x3f317218, v9
	v_max_f32_e32 v9, v94, v94
	v_max_f32_e32 v9, 0, v9
	v_fmac_f32_e32 v9, 0x3f317218, v11
	s_or_b64 s[84:85], s[26:27], s[84:85]
	v_cndmask_b32_e64 v194, 0, -v9, s[84:85]
	v_add_u32_e32 v9, 0x9b, v8
	v_add_u32_e32 v8, 0xbb, v8
	v_cmp_lt_i32_e64 s[88:89], v8, v164
	v_mul_f32_e64 v8, |v111|, s3
	s_or_b64 s[82:83], s[26:27], s[82:83]
	v_exp_f32_e32 v8, v8
	v_cndmask_b32_e64 v193, 0, -v10, s[82:83]
	v_mul_f32_e64 v10, |v95|, s3
	v_exp_f32_e32 v10, v10
	v_add_f32_e32 v8, 1.0, v8
	v_log_f32_e32 v8, v8
	s_mov_b64 s[16:17], s[86:87]
	v_add_f32_e32 v10, 1.0, v10
	v_cmp_lt_i32_e64 s[86:87], v9, v164
	v_max_f32_e32 v9, v111, v111
	v_log_f32_e32 v10, v10
	v_max_f32_e32 v9, 0, v9
	v_fmac_f32_e32 v9, 0x3f317218, v8
	v_max_f32_e32 v8, v95, v95
	v_max_f32_e32 v8, 0, v8
	v_fmac_f32_e32 v8, 0x3f317218, v10
	s_or_b64 s[86:87], s[26:27], s[86:87]
	s_or_b64 s[88:89], s[26:27], s[88:89]
	v_cndmask_b32_e64 v195, 0, -v9, s[86:87]
	v_cndmask_b32_e64 v196, 0, -v8, s[88:89]
	v_add_f32_e32 v8, v0, v2
	v_add_f32_e32 v9, v4, v6
	v_add_f32_e32 v8, v8, v9
	v_add_f32_e32 v9, v3, v5
	v_add_f32_e32 v10, v7, v15
	v_add_f32_e32 v10, v9, v10
	v_add_f32_e32 v9, v169, v176
	v_add_f32_e32 v11, v177, v179
	v_add_f32_e32 v9, v9, v11
	v_add_f32_e32 v11, v171, v173
	v_add_f32_e32 v12, v178, v180
	v_add_f32_e32 v11, v11, v12
	v_add_f32_e32 v12, v181, v183
	v_add_f32_e32 v13, v185, v187
	v_add_f32_e32 v12, v12, v13
	v_add_f32_e32 v13, v182, v184
	v_add_f32_e32 v14, v186, v188
	v_add_f32_e32 v152, v13, v14
	v_add_f32_e32 v13, v189, v191
	v_add_f32_e32 v14, v193, v195
	v_add_f32_e32 v13, v13, v14
	v_add_f32_e32 v14, v190, v192
	v_add_f32_e32 v170, v194, v196
	v_add_f32_e32 v175, v14, v170
	v_mov_b32_e32 v174, v11
	s_nop 1
	v_permlane32_swap_b32_e32 v11, v174
	v_mov_b32_e32 v204, v175
	v_add_f32_e32 v11, v11, v174
	v_cndmask_b32_e64 v202, 0, v174, s[38:39]
	v_mov_b32_e32 v174, v152
	v_permlane32_swap_b32_e32 v175, v204
	s_nop 0
	v_permlane32_swap_b32_e32 v152, v174
	v_add_f32_e32 v175, v175, v204
	v_cndmask_b32_e64 v204, 0, v204, s[38:39]
	v_cndmask_b32_e64 v203, 0, v174, s[38:39]
	v_add_f32_e32 v204, v153, v204
	v_pk_add_f32 v[152:153], v[152:153], v[174:175]
	v_mov_b32_e32 v172, v13
	v_add_f32_e32 v174, v203, v153
	v_pk_add_f32 v[152:153], v[152:153], v[152:153] op_sel:[0,1] op_sel_hi:[1,0]
	v_permlane32_swap_b32_e32 v13, v172
	v_add_f32_e32 v153, v202, v152
	v_add_f32_e32 v153, v180, v153
	v_add_f32_e32 v13, v13, v172
	v_cndmask_b32_e64 v200, 0, v172, s[38:39]
	v_mov_b32_e32 v172, v10
	v_add_f32_e32 v178, v178, v153
	s_nop 0
	v_permlane32_swap_b32_e32 v10, v172
	v_add_f32_e32 v180, v173, v178
	v_mov_b32_e32 v173, v152
	v_cndmask_b32_e64 v201, 0, v172, s[38:39]
	v_pk_add_f32 v[10:11], v[10:11], v[172:173]
	v_mov_b32_e32 v170, v9
	v_add_f32_e32 v152, v201, v11
	s_nop 0
	v_permlane32_swap_b32_e32 v9, v170
	v_add_f32_e32 v152, v15, v152
	v_add_f32_e32 v9, v9, v170
	v_cndmask_b32_e64 v198, 0, v170, s[38:39]
	v_mov_b32_e32 v170, v12
	v_add_f32_e32 v174, v188, v174
	v_add_f32_e32 v7, v7, v152
	v_pk_add_f32 v[10:11], v[10:11], v[10:11] op_sel:[0,1] op_sel_hi:[1,0]
	v_permlane32_swap_b32_e32 v12, v170
	v_add_f32_e32 v175, v186, v174
	v_add_f32_e32 v186, v171, v180
	v_add_f32_e32 v5, v5, v7
	v_add_f32_e32 v11, v200, v10
	v_mov_b32_e32 v171, v10
	v_cndmask_b32_e64 v199, 0, v170, s[38:39]
	v_add_f32_e32 v3, v3, v5
	v_add_f32_e32 v172, v195, v11
	v_pk_add_f32 v[10:11], v[12:13], v[170:171]
	v_add_f32_e32 v5, v81, v5
	v_mov_b32_e32 v14, v8
	v_add_f32_e32 v12, v199, v11
	v_pk_add_f32 v[10:11], v[10:11], v[10:11] op_sel:[0,1] op_sel_hi:[1,0]
	v_mul_f32_e32 v5, 0x3fb8aa3b, v5
	v_permlane32_swap_b32_e32 v8, v14
	v_mov_b32_e32 v15, v10
	v_exp_f32_e32 v5, v5
	v_cndmask_b32_e64 v197, 0, v14, s[38:39]
	v_pk_add_f32 v[8:9], v[8:9], v[14:15]
	v_add_f32_e32 v11, v198, v10
	v_add_f32_e32 v10, v197, v9
	v_add_f32_e32 v6, v6, v10
	v_add_f32_e32 v4, v4, v6
	v_add_f32_e32 v3, v80, v3
	v_cndmask_b32_e64 v14, 0, v5, s[4:5]
	v_add_f32_e32 v5, v99, v6
	v_add_f32_e32 v6, v83, v152
	v_mul_f32_e32 v3, 0x3fb8aa3b, v3
	v_mul_f32_e32 v6, 0x3fb8aa3b, v6
	v_exp_f32_e32 v3, v3
	v_exp_f32_e32 v6, v6
	v_add_f32_e32 v11, v179, v11
	v_add_f32_e32 v177, v177, v11
	v_add_f32_e32 v176, v176, v177
	v_add_f32_e32 v2, v2, v4
	v_cndmask_b32_e64 v10, 0, v3, s[0:1]
	v_add_f32_e32 v3, v98, v4
	v_add_f32_e32 v4, v82, v7
	v_cndmask_b32_e64 v80, 0, v6, s[12:13]
	v_add_f32_e32 v6, v84, v186
	v_add_f32_e32 v7, v101, v176
	v_mul_f32_e32 v4, 0x3fb8aa3b, v4
	v_mul_f32_e32 v5, 0x3fb8aa3b, v5
	v_mul_f32_e32 v6, 0x3fb8aa3b, v6
	v_mul_f32_e32 v7, 0x3fb8aa3b, v7
	v_exp_f32_e32 v4, v4
	v_exp_f32_e32 v5, v5
	v_exp_f32_e32 v6, v6
	v_exp_f32_e32 v7, v7
	v_add_f32_e32 v196, v196, v204
	v_add_f32_e32 v12, v187, v12
	v_add_f32_e32 v194, v194, v196
	v_add_f32_e32 v173, v193, v172
	v_add_f32_e32 v13, v185, v12
	v_add_f32_e32 v192, v192, v194
	v_add_f32_e32 v184, v184, v175
	v_add_f32_e32 v188, v191, v173
	v_add_f32_e32 v170, v183, v13
	v_add_f32_e32 v169, v169, v176
	v_add_f32_e32 v190, v190, v192
	v_add_f32_e32 v182, v182, v184
	v_add_f32_e32 v189, v189, v188
	v_add_f32_e32 v171, v181, v170
	v_add_f32_e32 v0, v0, v2
	v_add_f32_e32 v2, v97, v2
	v_cndmask_b32_e64 v15, 0, v4, s[8:9]
	v_cndmask_b32_e64 v4, 0, v5, s[10:11]
	v_add_f32_e32 v5, v100, v169
	v_add_f32_e32 v81, v85, v180
	v_cndmask_b32_e64 v82, 0, v6, s[44:45]
	v_cndmask_b32_e64 v6, 0, v7, s[46:47]
	v_add_f32_e32 v7, v102, v177
	v_add_f32_e32 v83, v86, v178
	v_add_f32_e32 v11, v103, v11
	v_add_f32_e32 v13, v106, v13
	v_add_f32_e32 v12, v107, v12
	v_add_f32_e32 v0, v96, v0
	v_mul_f32_e32 v2, 0x3fb8aa3b, v2
	v_mul_f32_e32 v3, 0x3fb8aa3b, v3
	v_mul_f32_e32 v5, 0x3fb8aa3b, v5
	v_mul_f32_e32 v81, 0x3fb8aa3b, v81
	v_mul_f32_e32 v7, 0x3fb8aa3b, v7
	v_mul_f32_e32 v83, 0x3fb8aa3b, v83
	v_mul_f32_e32 v11, 0x3fb8aa3b, v11
	v_add_f32_e32 v84, v87, v153
	v_add_f32_e32 v85, v104, v171
	v_add_f32_e32 v86, v88, v182
	v_add_f32_e32 v87, v105, v170
	v_add_f32_e32 v88, v89, v184
	v_mul_f32_e32 v13, 0x3fb8aa3b, v13
	v_add_f32_e32 v89, v90, v175
	v_mul_f32_e32 v12, 0x3fb8aa3b, v12
	v_add_f32_e32 v90, v91, v174
	v_add_f32_e32 v91, v108, v189
	v_add_f32_e32 v92, v92, v190
	v_add_f32_e32 v96, v109, v188
	v_add_f32_e32 v93, v93, v192
	v_add_f32_e32 v97, v110, v173
	v_add_f32_e32 v94, v94, v194
	v_add_f32_e32 v98, v111, v172
	v_add_f32_e32 v95, v95, v196
	v_mul_f32_e32 v0, 0x3fb8aa3b, v0
	v_exp_f32_e32 v2, v2
	v_exp_f32_e32 v3, v3
	v_exp_f32_e32 v5, v5
	v_exp_f32_e32 v81, v81
	v_exp_f32_e32 v7, v7
	v_exp_f32_e32 v83, v83
	v_exp_f32_e32 v11, v11
	v_mul_f32_e32 v84, 0x3fb8aa3b, v84
	v_mul_f32_e32 v85, 0x3fb8aa3b, v85
	v_mul_f32_e32 v86, 0x3fb8aa3b, v86
	v_mul_f32_e32 v87, 0x3fb8aa3b, v87
	v_mul_f32_e32 v88, 0x3fb8aa3b, v88
	v_exp_f32_e32 v13, v13
	v_mul_f32_e32 v89, 0x3fb8aa3b, v89
	v_exp_f32_e32 v12, v12
	v_mul_f32_e32 v90, 0x3fb8aa3b, v90
	v_mul_f32_e32 v91, 0x3fb8aa3b, v91
	v_mul_f32_e32 v92, 0x3fb8aa3b, v92
	v_mul_f32_e32 v96, 0x3fb8aa3b, v96
	v_mul_f32_e32 v93, 0x3fb8aa3b, v93
	v_mul_f32_e32 v97, 0x3fb8aa3b, v97
	v_mul_f32_e32 v94, 0x3fb8aa3b, v94
	v_mul_f32_e32 v98, 0x3fb8aa3b, v98
	v_mul_f32_e32 v95, 0x3fb8aa3b, v95
	v_exp_f32_e32 v0, v0
	v_exp_f32_e32 v84, v84
	v_exp_f32_e32 v85, v85
	v_exp_f32_e32 v86, v86
	v_exp_f32_e32 v87, v87
	v_exp_f32_e32 v88, v88
	v_exp_f32_e32 v89, v89
	v_exp_f32_e32 v90, v90
	v_exp_f32_e32 v91, v91
	v_exp_f32_e32 v92, v92
	v_exp_f32_e32 v96, v96
	v_exp_f32_e32 v93, v93
	v_exp_f32_e32 v97, v97
	v_exp_f32_e32 v94, v94
	v_exp_f32_e32 v98, v98
	v_exp_f32_e32 v95, v95
	v_cndmask_b32_e64 v2, 0, v2, s[14:15]
	v_cndmask_b32_e64 v3, 0, v3, s[6:7]
	v_cndmask_b32_e64 v5, 0, v5, s[42:43]
	v_cndmask_b32_e64 v81, 0, v81, s[48:49]
	v_cndmask_b32_e64 v7, 0, v7, s[50:51]
	v_cndmask_b32_e64 v83, 0, v83, s[52:53]
	v_cndmask_b32_e64 v11, 0, v11, s[54:55]
	v_cndmask_b32_e64 v13, 0, v13, s[66:67]
	v_cndmask_b32_e64 v12, 0, v12, s[70:71]
	v_readlane_b32 s46, v255, 18
	v_readlane_b32 s44, v255, 16
	v_readlane_b32 s52, v255, 10
	s_mov_b32 s27, s36
	s_mov_b32 s36, s35
	v_cndmask_b32_e32 v0, 0, v0, vcc
	s_mov_b32 s7, s2
	v_cndmask_b32_e64 v84, 0, v84, s[56:57]
	v_readlane_b32 s57, v255, 15
	v_readlane_b32 s56, v255, 14
	v_cndmask_b32_e64 v85, 0, v85, s[58:59]
	v_cndmask_b32_e64 v86, 0, v86, s[60:61]
	v_cndmask_b32_e64 v87, 0, v87, s[62:63]
	v_cndmask_b32_e64 v88, 0, v88, s[64:65]
	v_cndmask_b32_e64 v89, 0, v89, s[68:69]
	v_cndmask_b32_e64 v90, 0, v90, s[72:73]
	v_cndmask_b32_e64 v91, 0, v91, s[74:75]
	v_cndmask_b32_e64 v92, 0, v92, s[76:77]
	v_cndmask_b32_e64 v96, 0, v96, s[78:79]
	v_cndmask_b32_e64 v93, 0, v93, s[80:81]
	v_cndmask_b32_e64 v97, 0, v97, s[82:83]
	v_cndmask_b32_e64 v94, 0, v94, s[84:85]
	s_mov_b32 s84, s21
	v_cndmask_b32_e64 v98, 0, v98, s[86:87]
	s_mov_b64 s[86:87], s[16:17]
	v_readlane_b32 s17, v255, 39
	v_readlane_b32 s16, v255, 20
	v_readlane_b32 s47, v255, 19
	v_readlane_b32 s45, v255, 17
	v_readlane_b32 s55, v255, 13
	v_readlane_b32 s54, v255, 12
	v_readlane_b32 s53, v255, 11
	v_cndmask_b32_e64 v95, 0, v95, s[88:89]
	v_add_f32_e32 v153, v8, v9
	v_cvt_pk_bf16_f32 v2, v0, v2
	v_cvt_pk_bf16_f32 v3, v3, v4
	v_cvt_pk_bf16_f32 v4, v5, v6
	v_cvt_pk_bf16_f32 v5, v7, v11
	v_cvt_pk_bf16_f32 v6, v85, v87
	v_cvt_pk_bf16_f32 v7, v13, v12
	v_cvt_pk_bf16_f32 v8, v91, v96
	v_cvt_pk_bf16_f32 v9, v97, v98
	v_cvt_pk_bf16_f32 v10, v10, v14
	v_cvt_pk_bf16_f32 v11, v15, v80
	v_cvt_pk_bf16_f32 v12, v82, v81
	v_cvt_pk_bf16_f32 v13, v83, v84
	v_cvt_pk_bf16_f32 v80, v86, v88
	v_cvt_pk_bf16_f32 v81, v89, v90
	v_cvt_pk_bf16_f32 v82, v92, v93
	v_cvt_pk_bf16_f32 v83, v94, v95
	s_mul_i32 s0, s93, 0xa100
	v_add_u32_e32 v0, s0, v159
	s_setprio 1
	ds_read_b64_tr_b16 v[84:85], v0 offset:0x0
	ds_read_b64_tr_b16 v[86:87], v0 offset:0x100
	ds_read_b64_tr_b16 v[88:89], v0 offset:0x1000
	ds_read_b64_tr_b16 v[90:91], v0 offset:0x1100
	ds_read_b64_tr_b16 v[92:93], v0 offset:0x2000
	ds_read_b64_tr_b16 v[94:95], v0 offset:0x2100
	ds_read_b64_tr_b16 v[96:97], v0 offset:0x3000
	ds_read_b64_tr_b16 v[98:99], v0 offset:0x3100
	s_waitcnt lgkmcnt(0)
	s_nop 0
	v_mfma_f32_32x32x16_bf16 v[16:31], v[2:5], v[84:87], v[16:31]
	ds_read_b64_tr_b16 v[84:85], v0 offset:0x200
	ds_read_b64_tr_b16 v[86:87], v0 offset:0x300
	v_mfma_f32_32x32x16_bf16 v[16:31], v[6:9], v[88:91], v[16:31]
	ds_read_b64_tr_b16 v[88:89], v0 offset:0x1200
	ds_read_b64_tr_b16 v[90:91], v0 offset:0x1300
	v_mfma_f32_32x32x16_bf16 v[16:31], v[10:13], v[92:95], v[16:31]
	ds_read_b64_tr_b16 v[92:93], v0 offset:0x2200
	ds_read_b64_tr_b16 v[94:95], v0 offset:0x2300
	v_mfma_f32_32x32x16_bf16 v[16:31], v[80:83], v[96:99], v[16:31]
	ds_read_b64_tr_b16 v[96:97], v0 offset:0x3200
	ds_read_b64_tr_b16 v[98:99], v0 offset:0x3300
	s_waitcnt lgkmcnt(0)
	v_mfma_f32_32x32x16_bf16 v[32:47], v[2:5], v[84:87], v[32:47]
	ds_read_b64_tr_b16 v[84:85], v0 offset:0x400
	ds_read_b64_tr_b16 v[86:87], v0 offset:0x500
	v_mfma_f32_32x32x16_bf16 v[32:47], v[6:9], v[88:91], v[32:47]
	ds_read_b64_tr_b16 v[88:89], v0 offset:0x1400
	ds_read_b64_tr_b16 v[90:91], v0 offset:0x1500
	v_mfma_f32_32x32x16_bf16 v[32:47], v[10:13], v[92:95], v[32:47]
	ds_read_b64_tr_b16 v[92:93], v0 offset:0x2400
	ds_read_b64_tr_b16 v[94:95], v0 offset:0x2500
	v_mfma_f32_32x32x16_bf16 v[32:47], v[80:83], v[96:99], v[32:47]
	ds_read_b64_tr_b16 v[96:97], v0 offset:0x3400
	ds_read_b64_tr_b16 v[98:99], v0 offset:0x3500
	s_waitcnt lgkmcnt(0)
	v_mfma_f32_32x32x16_bf16 v[48:63], v[2:5], v[84:87], v[48:63]
	ds_read_b64_tr_b16 v[84:85], v0 offset:0x600
	ds_read_b64_tr_b16 v[86:87], v0 offset:0x700
	v_mfma_f32_32x32x16_bf16 v[48:63], v[6:9], v[88:91], v[48:63]
	ds_read_b64_tr_b16 v[88:89], v0 offset:0x1600
	ds_read_b64_tr_b16 v[90:91], v0 offset:0x1700
	v_mfma_f32_32x32x16_bf16 v[48:63], v[10:13], v[92:95], v[48:63]
	ds_read_b64_tr_b16 v[92:93], v0 offset:0x2600
	ds_read_b64_tr_b16 v[94:95], v0 offset:0x2700
	v_mfma_f32_32x32x16_bf16 v[48:63], v[80:83], v[96:99], v[48:63]
	ds_read_b64_tr_b16 v[96:97], v0 offset:0x3600
	ds_read_b64_tr_b16 v[98:99], v0 offset:0x3700
	s_waitcnt lgkmcnt(0)
	v_mfma_f32_32x32x16_bf16 v[64:79], v[2:5], v[84:87], v[64:79]
	v_mfma_f32_32x32x16_bf16 v[64:79], v[6:9], v[88:91], v[64:79]
	v_mfma_f32_32x32x16_bf16 v[64:79], v[10:13], v[92:95], v[64:79]
	v_mfma_f32_32x32x16_bf16 v[64:79], v[80:83], v[96:99], v[64:79]
	s_setprio 0

.LBB0_1259:
	s_waitcnt vmcnt(0)
	s_mov_b32 s21, 0
	s_cmp_lt_i32 s20, 1
	v_cmp_gt_u32_e64 s[38:39], 32, v162
	s_barrier
	s_cbranch_scc1 .LBB0_1290
	s_waitcnt vmcnt(4)
	v_lshlrev_b32_e32 v2, 8, v174
	s_waitcnt vmcnt(3)
	v_bitop3_b32 v3, v175, v162, 15 bitop3:0x78
	v_lshl_add_u32 v176, v3, 4, v2
	v_add_u32_e32 v3, 2, v175
	v_bitop3_b32 v3, v3, v162, 15 bitop3:0x78
	v_lshl_add_u32 v177, v3, 4, v2
	v_add_u32_e32 v3, 4, v175
	v_bitop3_b32 v3, v3, v162, 15 bitop3:0x78
	v_lshl_add_u32 v178, v3, 4, v2
	v_add_u32_e32 v3, 6, v175
	v_bitop3_b32 v3, v3, v162, 15 bitop3:0x78
	v_lshl_add_u32 v179, v3, 4, v2
	s_waitcnt vmcnt(2)
	v_lshlrev_b32_e32 v4, 1, v162
	v_and_b32_e32 v0, 0x118, v0
	v_lshlrev_b32_e32 v2, 4, v162
	v_readlane_b32 s0, v254, 53
	s_waitcnt vmcnt(1)
	v_and_b32_e32 v5, 0xc0, v2
	v_lshl_add_u64 v[2:3], v[162:163], 2, s[8:9]
	v_lshl_add_u32 v163, v174, 2, s0
	v_and_or_b32 v0, v4, 32, v0
	s_add_i32 s0, 0, 0x6000
	v_add3_u32 v186, v5, s0, v0
	v_and_b32_e32 v225, 32, v162
	v_mad_u32_u24 v186, v225, 56, v186
	s_lshl_b32 s0, s94, 6
	s_ashr_i32 s1, s0, 31
	s_movk_i32 s8, 0xfd00
	s_add_i32 s30, s10, s55
	v_lshl_add_u64 v[2:3], s[0:1], 2, v[2:3]
	s_mov_b32 s9, -1
	s_add_i32 s27, s20, -2
	s_add_i32 s34, s30, 31
	v_lshl_add_u64 v[172:173], v[2:3], 0, s[8:9]
	s_lshl_b64 s[8:9], s[0:1], 10
	s_add_u32 s1, s8, s6
	s_addc_u32 s3, s9, s7
	s_or_b32 s1, s1, s2
	v_readlane_b32 s2, v254, 15
	v_mov_b32_e32 v14, v1
	v_mov_b32_e32 v15, v1
	s_add_u32 s6, s2, s1
	v_readlane_b32 s1, v254, 16
	v_mov_b32_e32 v0, v1
	v_mov_b32_e32 v2, v1
	v_mov_b32_e32 v3, v1
	v_mov_b32_e32 v4, v1
	v_mov_b32_e32 v5, v1
	s_waitcnt vmcnt(0)
	v_mov_b32_e32 v6, v1
	v_mov_b32_e32 v7, v1
	v_mov_b32_e32 v8, v1
	v_mov_b32_e32 v9, v1
	v_mov_b32_e32 v10, v1
	v_mov_b32_e32 v11, v1
	v_mov_b32_e32 v12, v1
	v_mov_b32_e32 v13, v1
	v_mov_b64_e32 v[78:79], v[14:15]
	v_mov_b64_e32 v[62:63], v[14:15]
	v_mov_b64_e32 v[46:47], v[14:15]
	v_mov_b64_e32 v[30:31], v[14:15]
	v_mov_b64_e32 v[94:95], v[14:15]
	s_mov_b32 s26, 2
	v_add_u32_e32 v180, s30, v174
	v_lshlrev_b32_e32 v181, 4, v175
	v_cmp_eq_u32_e64 s[40:41], 0, v162
	v_xor_b32_e32 v182, 0x80, v177
	v_xor_b32_e32 v183, 0x80, v176
	v_xor_b32_e32 v184, 0x80, v178
	v_xor_b32_e32 v185, 0x80, v179
	v_lshl_add_u32 v187, v175, 2, s0
	s_addc_u32 s7, s1, s3
	s_mov_b64 s[8:9], -1
	v_mov_b32_e32 v188, 0
	s_mov_b32 s1, 0
	v_mov_b64_e32 v[76:77], v[12:13]
	v_mov_b64_e32 v[74:75], v[10:11]
	v_mov_b64_e32 v[72:73], v[8:9]
	v_mov_b64_e32 v[70:71], v[6:7]
	v_mov_b64_e32 v[68:69], v[4:5]
	v_mov_b64_e32 v[66:67], v[2:3]
	v_mov_b64_e32 v[64:65], v[0:1]
	v_mov_b64_e32 v[60:61], v[12:13]
	v_mov_b64_e32 v[58:59], v[10:11]
	v_mov_b64_e32 v[56:57], v[8:9]
	v_mov_b64_e32 v[54:55], v[6:7]
	v_mov_b64_e32 v[52:53], v[4:5]
	v_mov_b64_e32 v[50:51], v[2:3]
	v_mov_b64_e32 v[48:49], v[0:1]
	v_mov_b64_e32 v[44:45], v[12:13]
	v_mov_b64_e32 v[42:43], v[10:11]
	v_mov_b64_e32 v[40:41], v[8:9]
	v_mov_b64_e32 v[38:39], v[6:7]
	v_mov_b64_e32 v[36:37], v[4:5]
	v_mov_b64_e32 v[34:35], v[2:3]
	v_mov_b64_e32 v[32:33], v[0:1]
	v_mov_b64_e32 v[28:29], v[12:13]
	v_mov_b64_e32 v[26:27], v[10:11]
	v_mov_b64_e32 v[24:25], v[8:9]
	v_mov_b64_e32 v[22:23], v[6:7]
	v_mov_b64_e32 v[20:21], v[4:5]
	v_mov_b64_e32 v[18:19], v[2:3]
	v_mov_b64_e32 v[16:17], v[0:1]
	v_mov_b32_e32 v96, 0
	v_mov_b64_e32 v[92:93], v[12:13]
	v_mov_b64_e32 v[90:91], v[10:11]
	v_mov_b64_e32 v[88:89], v[8:9]
	v_mov_b64_e32 v[86:87], v[6:7]
	v_mov_b64_e32 v[84:85], v[4:5]
	v_mov_b64_e32 v[82:83], v[2:3]
	v_mov_b64_e32 v[80:81], v[0:1]
	s_mov_b32 s25, 0
	s_mov_b32 s35, 0
	s_branch .LBB0_1263

.LBB0_1281:
	v_add_f32_e32 v121, v2, v3
	v_fmac_f32_e32 v121, v96, v108
	v_cvt_pk_bf16_f32 v2, v109, v112
	v_cvt_pk_bf16_f32 v3, v113, v114
	v_cvt_pk_bf16_f32 v4, v115, v110
	v_cvt_pk_bf16_f32 v5, v116, v117
	v_cvt_pk_bf16_f32 v106, v111, v106
	v_cvt_pk_bf16_f32 v107, v107, v102
	v_cvt_pk_bf16_f32 v108, v103, v118
	v_cvt_pk_bf16_f32 v109, v119, v120
	v_cvt_pk_bf16_f32 v98, v98, v99
	v_cvt_pk_bf16_f32 v99, v100, v101
	v_cvt_pk_bf16_f32 v100, v14, v15
	v_cvt_pk_bf16_f32 v101, v104, v105
	v_cvt_pk_bf16_f32 v6, v6, v7
	v_cvt_pk_bf16_f32 v7, v8, v9
	v_cvt_pk_bf16_f32 v8, v12, v13
	v_cvt_pk_bf16_f32 v9, v10, v11
	s_nop 0
	v_add_u32_e32 v14, s2, v186
	s_setprio 1
	ds_read_b64_tr_b16 v[10:11], v14 offset:0x0
	ds_read_b64_tr_b16 v[12:13], v14 offset:0x100
	ds_read_b64_tr_b16 v[102:103], v14 offset:0x1000
	ds_read_b64_tr_b16 v[104:105], v14 offset:0x1100
	ds_read_b64_tr_b16 v[110:111], v14 offset:0x2000
	ds_read_b64_tr_b16 v[112:113], v14 offset:0x2100
	ds_read_b64_tr_b16 v[114:115], v14 offset:0x3000
	ds_read_b64_tr_b16 v[116:117], v14 offset:0x3100
	s_waitcnt lgkmcnt(0)
	s_nop 0
	v_mfma_f32_32x32x16_bf16 v[64:79], v[2:5], v[10:13], v[64:79]
	ds_read_b64_tr_b16 v[10:11], v14 offset:0x200
	ds_read_b64_tr_b16 v[12:13], v14 offset:0x300
	v_mfma_f32_32x32x16_bf16 v[64:79], v[106:109], v[102:105], v[64:79]
	ds_read_b64_tr_b16 v[102:103], v14 offset:0x1200
	ds_read_b64_tr_b16 v[104:105], v14 offset:0x1300
	v_mfma_f32_32x32x16_bf16 v[64:79], v[98:101], v[110:113], v[64:79]
	ds_read_b64_tr_b16 v[110:111], v14 offset:0x2200
	ds_read_b64_tr_b16 v[112:113], v14 offset:0x2300
	v_mfma_f32_32x32x16_bf16 v[64:79], v[6:9], v[114:117], v[64:79]
	ds_read_b64_tr_b16 v[114:115], v14 offset:0x3200
	ds_read_b64_tr_b16 v[116:117], v14 offset:0x3300
	s_waitcnt lgkmcnt(0)
	v_mfma_f32_32x32x16_bf16 v[48:63], v[2:5], v[10:13], v[48:63]
	ds_read_b64_tr_b16 v[10:11], v14 offset:0x400
	ds_read_b64_tr_b16 v[12:13], v14 offset:0x500
	v_mfma_f32_32x32x16_bf16 v[48:63], v[106:109], v[102:105], v[48:63]
	ds_read_b64_tr_b16 v[102:103], v14 offset:0x1400
	ds_read_b64_tr_b16 v[104:105], v14 offset:0x1500
	v_mfma_f32_32x32x16_bf16 v[48:63], v[98:101], v[110:113], v[48:63]
	ds_read_b64_tr_b16 v[110:111], v14 offset:0x2400
	ds_read_b64_tr_b16 v[112:113], v14 offset:0x2500
	v_mfma_f32_32x32x16_bf16 v[48:63], v[6:9], v[114:117], v[48:63]
	ds_read_b64_tr_b16 v[114:115], v14 offset:0x3400
	ds_read_b64_tr_b16 v[116:117], v14 offset:0x3500
	s_waitcnt lgkmcnt(0)
	v_mfma_f32_32x32x16_bf16 v[32:47], v[2:5], v[10:13], v[32:47]
	ds_read_b64_tr_b16 v[10:11], v14 offset:0x600
	ds_read_b64_tr_b16 v[12:13], v14 offset:0x700
	v_mfma_f32_32x32x16_bf16 v[32:47], v[106:109], v[102:105], v[32:47]
	ds_read_b64_tr_b16 v[102:103], v14 offset:0x1600
	ds_read_b64_tr_b16 v[104:105], v14 offset:0x1700
	v_mfma_f32_32x32x16_bf16 v[32:47], v[98:101], v[110:113], v[32:47]
	ds_read_b64_tr_b16 v[110:111], v14 offset:0x2600
	ds_read_b64_tr_b16 v[112:113], v14 offset:0x2700
	v_mfma_f32_32x32x16_bf16 v[32:47], v[6:9], v[114:117], v[32:47]
	ds_read_b64_tr_b16 v[114:115], v14 offset:0x3600
	ds_read_b64_tr_b16 v[116:117], v14 offset:0x3700
	s_waitcnt lgkmcnt(0)
	v_mfma_f32_32x32x16_bf16 v[16:31], v[2:5], v[10:13], v[16:31]
	v_mfma_f32_32x32x16_bf16 v[16:31], v[106:109], v[102:105], v[16:31]
	v_mfma_f32_32x32x16_bf16 v[16:31], v[98:101], v[110:113], v[16:31]
	v_mfma_f32_32x32x16_bf16 v[16:31], v[6:9], v[114:117], v[16:31]
	s_setprio 0
	v_mov_b32_e32 v96, v121
